# P5 mixer-prep: batch the serialized per-step global loads (prep_moba q/k + V^T loops, prep_gdn conv loop) into up-front prefetch with counted vmcnt; P7 scan loader: relaxed over-conservative vmcnt
# speedup vs baseline: 1.0104x; 1.0104x over previous
.LBB0_530:
	s_or_b64 exec, exec, s[8:9]
	v_fmamk_f32 v45, v45, 0x3c000000, v75
	v_pk_add_f32 v[46:47], v[46:47], v[50:51]
	v_cmp_gt_f32_e32 vcc, s40, v45
	v_mul_f32_e32 v50, 0x4f800000, v45
	v_pk_add_f32 v[48:49], v[48:49], v[52:53]
	v_cndmask_b32_e32 v45, v45, v50, vcc
	v_sqrt_f32_e32 v50, v45
	v_pk_add_f32 v[46:47], v[46:47], v[60:61]
	s_nop 0
	v_mov_b32_e32 v61, v4
	v_mov_b32_e32 v4, v3
	v_add_u32_e32 v51, -1, v50
	v_fma_f32 v52, -v51, v50, v45
	v_cmp_ge_f32_e64 s[8:9], 0, v52
	v_add_u32_e32 v52, 1, v50
	v_pk_add_f32 v[48:49], v[48:49], v[62:63]
	v_cndmask_b32_e64 v51, v50, v51, s[8:9]
	v_fma_f32 v50, -v52, v50, v45
	v_cmp_lt_f32_e64 s[8:9], 0, v50
	s_add_u32 s30, s30, 0x38000
	v_pk_add_f32 v[46:47], v[46:47], v[68:69]
	v_cndmask_b32_e64 v50, v51, v52, s[8:9]
	v_mul_f32_e32 v51, 0x37800000, v50
	v_cndmask_b32_e32 v50, v50, v51, vcc
	v_cmp_class_f32_e32 vcc, v45, v76
	v_pk_add_f32 v[48:49], v[48:49], v[70:71]
	s_addc_u32 s31, s31, 0
	v_cndmask_b32_e32 v45, v50, v45, vcc
	v_div_scale_f32 v50, s[8:9], v45, v45, 1.0
	v_rcp_f32_e32 v51, v50
	v_add_u32_e32 v29, 0x200, v29
	v_add_u32_e32 v78, 0x200, v78
	s_cmp_eq_u32 s30, 0xe0000
	v_fma_f32 v52, -v50, v51, 1.0
	v_fmac_f32_e32 v51, v52, v51
	v_div_scale_f32 v52, vcc, 1.0, v45, 1.0
	v_mul_f32_e32 v53, v52, v51
	v_fma_f32 v60, -v50, v53, v52
	v_fmac_f32_e32 v53, v60, v51
	v_fma_f32 v50, -v50, v53, v52
	v_div_fmas_f32 v50, v50, v51, v53
	v_div_fixup_f32 v50, v50, v45, 1.0
	v_pk_mul_f32 v[52:53], v[50:51], v[66:67] op_sel_hi:[0,1]
	v_pk_mul_f32 v[50:51], v[50:51], v[64:65] op_sel_hi:[0,1]
	v_pk_mul_f32 v[52:53], v[30:31], v[52:53]
	v_pk_mul_f32 v[50:51], v[32:33], v[50:51]
	v_mov_b32_e32 v60, v2
	v_pk_mul_f32 v[2:3], v[4:5], v[50:51]
	v_pk_mul_f32 v[4:5], v[4:5], v[52:53]
	v_pk_fma_f32 v[2:3], v[60:61], v[52:53], v[2:3] neg_lo:[0,0,1] neg_hi:[0,0,1]
	v_pk_fma_f32 v[4:5], v[60:61], v[50:51], v[4:5]
	v_add_u32_e32 v50, 0x300, v44
	v_ashrrev_i32_e32 v51, 31, v50
	v_cvt_pk_bf16_f32 v45, v2, v3
	v_lshl_add_u64 v[50:51], v[50:51], 1, v[34:35]
	global_store_dword v[50:51], v45, off
	v_cvt_pk_bf16_f32 v45, v4, v5
	v_pk_add_f32 v[46:47], v[46:47], v[2:3]
	v_pk_add_f32 v[48:49], v[48:49], v[4:5]
	v_add_u32_e32 v44, 0x400, v44
	global_store_dword v[50:51], v45, off offset:128
	s_cbranch_scc1 .LBB0_547
.LBB0_531:
	v_lshl_add_u64 v[116:117], v[42:43], 0, s[30:31]
	v_add_co_u32_e32 v116, vcc, 0x26400000, v116
	s_nop 1
	v_addc_co_u32_e32 v117, vcc, 0, v117, vcc
	global_load_dword v84, v[116:117], off
	global_load_dword v85, v[116:117], off offset:128
	v_add_u32_e32 v118, v6, v78
	v_ashrrev_i32_e32 v119, 31, v118
	v_lshl_add_u64 v[118:119], v[118:119], 3, s[18:19]
	global_load_dwordx4 v[86:89], v[118:119], off
	v_lshl_add_u64 v[116:117], v[40:41], 0, s[30:31]
	v_add_co_u32_e32 v116, vcc, s39, v116
	s_nop 1
	v_addc_co_u32_e32 v117, vcc, 0, v117, vcc
	global_load_dword v90, v[116:117], off
	global_load_dword v91, v[116:117], off offset:128
	v_add_u32_e32 v118, v6, v29
	v_add_u32_e32 v118, 0x80, v118
	v_ashrrev_i32_e32 v119, 31, v118
	v_lshl_add_u64 v[118:119], v[118:119], 3, s[18:19]
	global_load_dwordx4 v[92:95], v[118:119], off
	v_lshl_add_u64 v[116:117], v[38:39], 0, s[30:31]
	v_add_co_u32_e32 v116, vcc, s39, v116
	s_nop 1
	v_addc_co_u32_e32 v117, vcc, 0, v117, vcc
	global_load_dword v96, v[116:117], off
	global_load_dword v97, v[116:117], off offset:128
	v_add_u32_e32 v118, v6, v29
	v_add_u32_e32 v118, 0x100, v118
	v_ashrrev_i32_e32 v119, 31, v118
	v_lshl_add_u64 v[118:119], v[118:119], 3, s[18:19]
	global_load_dwordx4 v[98:101], v[118:119], off
	v_lshl_add_u64 v[116:117], v[36:37], 0, s[30:31]
	v_add_co_u32_e32 v116, vcc, s39, v116
	s_nop 1
	v_addc_co_u32_e32 v117, vcc, 0, v117, vcc
	global_load_dword v102, v[116:117], off
	global_load_dword v103, v[116:117], off offset:128
	v_add_u32_e32 v118, v6, v29
	v_add_u32_e32 v118, 0x180, v118
	v_ashrrev_i32_e32 v119, 31, v118
	v_lshl_add_u64 v[118:119], v[118:119], 3, s[18:19]
	global_load_dwordx4 v[104:107], v[118:119], off
	v_lshl_add_u64 v[2:3], v[42:43], 0, s[30:31]
	v_add_co_u32_e32 v2, vcc, 0x26400000, v2
	s_nop 1
	v_addc_co_u32_e32 v3, vcc, 0, v3, vcc
	v_add_u32_e32 v2, v6, v78
	v_ashrrev_i32_e32 v3, 31, v2
	v_lshl_add_u64 v[2:3], v[2:3], 3, s[18:19]
	s_waitcnt vmcnt(9)
	v_mov_b32_e32 v45, v84
	v_mov_b32_e32 v51, v85
	v_mov_b32_e32 v2, v86
	v_mov_b32_e32 v3, v87
	v_mov_b32_e32 v4, v88
	v_mov_b32_e32 v5, v89
	v_lshlrev_b32_e32 v52, 16, v45
	v_and_b32_e32 v53, 0xffff0000, v45
	s_nop 0
	v_lshlrev_b32_e32 v50, 16, v51
	v_and_b32_e32 v51, 0xffff0000, v51
	v_pk_mul_f32 v[60:61], v[52:53], v[52:53]
	v_pk_mul_f32 v[62:63], v[50:51], v[50:51]
	v_add_f32_e32 v60, v60, v61
	v_add_f32_e32 v45, v62, v63
	v_add_f32_e32 v45, v60, v45
	v_mov_b32_e32 v60, 0
	s_nop 0
	v_add_f32_dpp v45, v45, v45 quad_perm:[1,0,3,2] row_mask:0xf bank_mask:0xf bound_ctrl:1
	s_nop 1
	v_add_f32_dpp v45, v45, v45 quad_perm:[2,3,0,1] row_mask:0xf bank_mask:0xf bound_ctrl:1
	s_nop 1
	v_add_f32_dpp v45, v45, v45 row_half_mirror row_mask:0xf bank_mask:0xf bound_ctrl:1
	s_nop 1
	v_add_f32_dpp v45, v45, v45 row_mirror row_mask:0xf bank_mask:0xf bound_ctrl:1
	s_nop 1
	v_mov_b32_dpp v60, v45 row_bcast:15 row_mask:0xa bank_mask:0xf bound_ctrl:1
	v_add_f32_e32 v45, v45, v60
	s_and_saveexec_b64 s[8:9], s[4:5]
	s_xor_b64 s[8:9], exec, s[8:9]
	s_cbranch_execz .LBB0_533
	v_readlane_b32 s52, v45, 63

.LBB0_535:
	s_or_b64 exec, exec, s[8:9]
	v_fmamk_f32 v45, v60, 0x3c000000, v75
	v_mul_f32_e32 v60, 0x4f800000, v45
	v_cmp_gt_f32_e32 vcc, s40, v45
	s_nop 1
	v_cndmask_b32_e32 v45, v45, v60, vcc
	v_sqrt_f32_e32 v60, v45
	s_nop 0
	v_add_u32_e32 v61, -1, v60
	v_fma_f32 v63, -v61, v60, v45
	v_add_u32_e32 v62, 1, v60
	v_cmp_ge_f32_e64 s[8:9], 0, v63
	s_nop 1
	v_cndmask_b32_e64 v61, v60, v61, s[8:9]
	v_fma_f32 v60, -v62, v60, v45
	v_cmp_lt_f32_e64 s[8:9], 0, v60
	s_nop 1
	v_cndmask_b32_e64 v60, v61, v62, s[8:9]
	v_mul_f32_e32 v61, 0x37800000, v60
	v_cndmask_b32_e32 v60, v60, v61, vcc
	v_cmp_class_f32_e32 vcc, v45, v76
	s_nop 1
	v_cndmask_b32_e32 v45, v60, v45, vcc
	v_div_scale_f32 v60, s[8:9], v45, v45, 1.0
	v_rcp_f32_e32 v61, v60
	s_nop 0
	v_fma_f32 v62, -v60, v61, 1.0
	v_fmac_f32_e32 v61, v62, v61
	v_div_scale_f32 v62, vcc, 1.0, v45, 1.0
	v_mul_f32_e32 v63, v62, v61
	v_fma_f32 v64, -v60, v63, v62
	v_fmac_f32_e32 v63, v64, v61
	v_fma_f32 v60, -v60, v63, v62
	v_div_fmas_f32 v60, v60, v61, v63
	v_div_fixup_f32 v60, v60, v45, 1.0
	v_pk_mul_f32 v[50:51], v[60:61], v[50:51] op_sel_hi:[0,1]
	v_pk_mul_f32 v[52:53], v[60:61], v[52:53] op_sel_hi:[0,1]
	v_pk_mul_f32 v[60:61], v[32:33], v[50:51]
	s_nop 0
	v_mov_b32_e32 v63, v4
	v_mov_b32_e32 v4, v3
	v_pk_mul_f32 v[52:53], v[30:31], v[52:53]
	v_mov_b32_e32 v62, v2
	v_pk_mul_f32 v[2:3], v[4:5], v[60:61]
	v_ashrrev_i32_e32 v45, 31, v44
	v_pk_fma_f32 v[50:51], v[62:63], v[52:53], v[2:3] neg_lo:[0,0,1] neg_hi:[0,0,1]
	v_pk_mul_f32 v[2:3], v[4:5], v[52:53]
	v_cvt_pk_bf16_f32 v4, v50, v51
	v_pk_fma_f32 v[52:53], v[62:63], v[60:61], v[2:3]
	v_lshl_add_u64 v[2:3], v[44:45], 1, v[34:35]
	global_store_dword v[2:3], v4, off
	v_cvt_pk_bf16_f32 v4, v52, v53
	global_store_dword v[2:3], v4, off offset:128
	v_lshl_add_u64 v[2:3], v[40:41], 0, s[30:31]
	v_add_co_u32_e32 v2, vcc, s39, v2
	v_add_u32_e32 v45, v6, v29
	s_nop 0
	v_addc_co_u32_e32 v3, vcc, 0, v3, vcc
	v_add_u32_e32 v2, 0x80, v45
	v_ashrrev_i32_e32 v3, 31, v2
	v_lshl_add_u64 v[2:3], v[2:3], 3, s[18:19]
	s_waitcnt vmcnt(8)
	v_mov_b32_e32 v60, v90
	v_mov_b32_e32 v61, v91
	v_mov_b32_e32 v2, v92
	v_mov_b32_e32 v3, v93
	v_mov_b32_e32 v4, v94
	v_mov_b32_e32 v5, v95
	v_lshlrev_b32_e32 v62, 16, v60
	v_and_b32_e32 v63, 0xffff0000, v60
	s_nop 0
	v_lshlrev_b32_e32 v60, 16, v61
	v_and_b32_e32 v61, 0xffff0000, v61
	v_pk_mul_f32 v[64:65], v[62:63], v[62:63]
	v_pk_mul_f32 v[66:67], v[60:61], v[60:61]
	v_add_f32_e32 v64, v64, v65
	v_add_f32_e32 v66, v66, v67
	v_add_f32_e32 v64, v64, v66
	v_mov_b32_e32 v65, 0
	s_nop 0
	v_add_f32_dpp v64, v64, v64 quad_perm:[1,0,3,2] row_mask:0xf bank_mask:0xf bound_ctrl:1
	s_nop 1
	v_add_f32_dpp v64, v64, v64 quad_perm:[2,3,0,1] row_mask:0xf bank_mask:0xf bound_ctrl:1
	s_nop 1
	v_add_f32_dpp v64, v64, v64 row_half_mirror row_mask:0xf bank_mask:0xf bound_ctrl:1
	s_nop 1
	v_add_f32_dpp v64, v64, v64 row_mirror row_mask:0xf bank_mask:0xf bound_ctrl:1
	s_nop 1
	v_mov_b32_dpp v65, v64 row_bcast:15 row_mask:0xa bank_mask:0xf bound_ctrl:1
	v_add_f32_e32 v64, v64, v65
	s_and_saveexec_b64 s[8:9], s[4:5]
	s_xor_b64 s[8:9], exec, s[8:9]
	s_cbranch_execz .LBB0_537
	v_readlane_b32 s52, v64, 63

.LBB0_539:
	s_or_b64 exec, exec, s[8:9]
	v_fmamk_f32 v64, v65, 0x3c000000, v75
	v_mul_f32_e32 v65, 0x4f800000, v64
	v_cmp_gt_f32_e32 vcc, s40, v64
	s_nop 1
	v_cndmask_b32_e32 v64, v64, v65, vcc
	v_sqrt_f32_e32 v65, v64
	s_nop 0
	v_add_u32_e32 v66, -1, v65
	v_fma_f32 v68, -v66, v65, v64
	v_add_u32_e32 v67, 1, v65
	v_cmp_ge_f32_e64 s[8:9], 0, v68
	s_nop 1
	v_cndmask_b32_e64 v66, v65, v66, s[8:9]
	v_fma_f32 v65, -v67, v65, v64
	v_cmp_lt_f32_e64 s[8:9], 0, v65
	s_nop 1
	v_cndmask_b32_e64 v65, v66, v67, s[8:9]
	v_mul_f32_e32 v66, 0x37800000, v65
	v_cndmask_b32_e32 v65, v65, v66, vcc
	v_cmp_class_f32_e32 vcc, v64, v76
	s_nop 1
	v_cndmask_b32_e32 v64, v65, v64, vcc
	v_div_scale_f32 v65, s[8:9], v64, v64, 1.0
	v_rcp_f32_e32 v66, v65
	s_nop 0
	v_fma_f32 v67, -v65, v66, 1.0
	v_fmac_f32_e32 v66, v67, v66
	v_div_scale_f32 v67, vcc, 1.0, v64, 1.0
	v_mul_f32_e32 v68, v67, v66
	v_fma_f32 v69, -v65, v68, v67
	v_fmac_f32_e32 v68, v69, v66
	v_fma_f32 v65, -v65, v68, v67
	v_div_fmas_f32 v65, v65, v66, v68
	v_div_fixup_f32 v64, v65, v64, 1.0
	v_pk_mul_f32 v[60:61], v[64:65], v[60:61] op_sel_hi:[0,1]
	v_pk_mul_f32 v[62:63], v[64:65], v[62:63] op_sel_hi:[0,1]
	v_pk_mul_f32 v[64:65], v[32:33], v[60:61]
	s_nop 0
	v_mov_b32_e32 v67, v4
	v_mov_b32_e32 v4, v3
	v_pk_mul_f32 v[62:63], v[30:31], v[62:63]
	v_mov_b32_e32 v66, v2
	v_pk_mul_f32 v[2:3], v[4:5], v[64:65]
	s_nop 0
	v_pk_fma_f32 v[60:61], v[66:67], v[62:63], v[2:3] neg_lo:[0,0,1] neg_hi:[0,0,1]
	v_pk_mul_f32 v[2:3], v[4:5], v[62:63]
	v_cvt_pk_bf16_f32 v4, v60, v61
	v_pk_fma_f32 v[62:63], v[66:67], v[64:65], v[2:3]
	v_add_u32_e32 v2, 0x100, v44
	v_ashrrev_i32_e32 v3, 31, v2
	v_lshl_add_u64 v[2:3], v[2:3], 1, v[34:35]
	global_store_dword v[2:3], v4, off
	v_cvt_pk_bf16_f32 v4, v62, v63
	global_store_dword v[2:3], v4, off offset:128
	v_lshl_add_u64 v[2:3], v[38:39], 0, s[30:31]
	v_add_co_u32_e32 v2, vcc, s39, v2
	s_nop 1
	v_addc_co_u32_e32 v3, vcc, 0, v3, vcc
	v_add_u32_e32 v2, 0x100, v45
	v_ashrrev_i32_e32 v3, 31, v2
	v_lshl_add_u64 v[2:3], v[2:3], 3, s[18:19]
	s_waitcnt vmcnt(7)
	v_mov_b32_e32 v64, v96
	v_mov_b32_e32 v65, v97
	v_mov_b32_e32 v2, v98
	v_mov_b32_e32 v3, v99
	v_mov_b32_e32 v4, v100
	v_mov_b32_e32 v5, v101
	v_lshlrev_b32_e32 v66, 16, v64
	v_and_b32_e32 v67, 0xffff0000, v64
	s_nop 0
	v_lshlrev_b32_e32 v64, 16, v65
	v_and_b32_e32 v65, 0xffff0000, v65
	v_pk_mul_f32 v[68:69], v[66:67], v[66:67]
	v_pk_mul_f32 v[70:71], v[64:65], v[64:65]
	v_add_f32_e32 v68, v68, v69
	v_add_f32_e32 v70, v70, v71
	v_add_f32_e32 v68, v68, v70
	v_mov_b32_e32 v69, 0
	s_nop 0
	v_add_f32_dpp v68, v68, v68 quad_perm:[1,0,3,2] row_mask:0xf bank_mask:0xf bound_ctrl:1
	s_nop 1
	v_add_f32_dpp v68, v68, v68 quad_perm:[2,3,0,1] row_mask:0xf bank_mask:0xf bound_ctrl:1
	s_nop 1
	v_add_f32_dpp v68, v68, v68 row_half_mirror row_mask:0xf bank_mask:0xf bound_ctrl:1
	s_nop 1
	v_add_f32_dpp v68, v68, v68 row_mirror row_mask:0xf bank_mask:0xf bound_ctrl:1
	s_nop 1
	v_mov_b32_dpp v69, v68 row_bcast:15 row_mask:0xa bank_mask:0xf bound_ctrl:1
	v_add_f32_e32 v68, v68, v69
	s_and_saveexec_b64 s[8:9], s[4:5]
	s_xor_b64 s[8:9], exec, s[8:9]
	s_cbranch_execz .LBB0_541
	v_readlane_b32 s52, v68, 63

.LBB0_543:
	s_or_b64 exec, exec, s[8:9]
	v_fmamk_f32 v68, v69, 0x3c000000, v75
	v_mul_f32_e32 v69, 0x4f800000, v68
	v_cmp_gt_f32_e32 vcc, s40, v68
	s_nop 1
	v_cndmask_b32_e32 v68, v68, v69, vcc
	v_sqrt_f32_e32 v69, v68
	s_nop 0
	v_add_u32_e32 v70, -1, v69
	v_fma_f32 v79, -v70, v69, v68
	v_add_u32_e32 v71, 1, v69
	v_cmp_ge_f32_e64 s[8:9], 0, v79
	s_nop 1
	v_cndmask_b32_e64 v70, v69, v70, s[8:9]
	v_fma_f32 v69, -v71, v69, v68
	v_cmp_lt_f32_e64 s[8:9], 0, v69
	s_nop 1
	v_cndmask_b32_e64 v69, v70, v71, s[8:9]
	v_mul_f32_e32 v70, 0x37800000, v69
	v_cndmask_b32_e32 v69, v69, v70, vcc
	v_cmp_class_f32_e32 vcc, v68, v76
	s_nop 1
	v_cndmask_b32_e32 v68, v69, v68, vcc
	v_div_scale_f32 v69, s[8:9], v68, v68, 1.0
	v_rcp_f32_e32 v70, v69
	s_nop 0
	v_fma_f32 v71, -v69, v70, 1.0
	v_fmac_f32_e32 v70, v71, v70
	v_div_scale_f32 v71, vcc, 1.0, v68, 1.0
	v_mul_f32_e32 v79, v71, v70
	v_fma_f32 v80, -v69, v79, v71
	v_fmac_f32_e32 v79, v80, v70
	v_fma_f32 v69, -v69, v79, v71
	v_div_fmas_f32 v69, v69, v70, v79
	v_div_fixup_f32 v68, v69, v68, 1.0
	v_pk_mul_f32 v[64:65], v[68:69], v[64:65] op_sel_hi:[0,1]
	v_pk_mul_f32 v[66:67], v[68:69], v[66:67] op_sel_hi:[0,1]
	v_pk_mul_f32 v[64:65], v[32:33], v[64:65]
	s_nop 0
	v_mov_b32_e32 v71, v4
	v_mov_b32_e32 v4, v3
	v_pk_mul_f32 v[66:67], v[30:31], v[66:67]
	v_mov_b32_e32 v70, v2
	v_pk_mul_f32 v[2:3], v[4:5], v[64:65]
	s_nop 0
	v_pk_fma_f32 v[68:69], v[70:71], v[66:67], v[2:3] neg_lo:[0,0,1] neg_hi:[0,0,1]
	v_pk_mul_f32 v[2:3], v[4:5], v[66:67]
	v_cvt_pk_bf16_f32 v4, v68, v69
	v_pk_fma_f32 v[70:71], v[70:71], v[64:65], v[2:3]
	v_add_u32_e32 v2, 0x200, v44
	v_ashrrev_i32_e32 v3, 31, v2
	v_lshl_add_u64 v[2:3], v[2:3], 1, v[34:35]
	global_store_dword v[2:3], v4, off
	v_cvt_pk_bf16_f32 v4, v70, v71
	global_store_dword v[2:3], v4, off offset:128
	v_lshl_add_u64 v[2:3], v[36:37], 0, s[30:31]
	v_add_co_u32_e32 v2, vcc, s39, v2
	s_nop 1
	v_addc_co_u32_e32 v3, vcc, 0, v3, vcc
	v_add_u32_e32 v2, 0x180, v45
	v_ashrrev_i32_e32 v3, 31, v2
	v_lshl_add_u64 v[2:3], v[2:3], 3, s[18:19]
	s_waitcnt vmcnt(6)
	v_mov_b32_e32 v64, v102
	v_mov_b32_e32 v65, v103
	v_mov_b32_e32 v2, v104
	v_mov_b32_e32 v3, v105
	v_mov_b32_e32 v4, v106
	v_mov_b32_e32 v5, v107
	v_lshlrev_b32_e32 v66, 16, v64
	v_and_b32_e32 v67, 0xffff0000, v64
	s_nop 0
	v_lshlrev_b32_e32 v64, 16, v65
	v_and_b32_e32 v65, 0xffff0000, v65
	v_pk_mul_f32 v[80:81], v[66:67], v[66:67]
	v_pk_mul_f32 v[82:83], v[64:65], v[64:65]
	v_add_f32_e32 v79, v80, v81
	v_add_f32_e32 v45, v82, v83
	v_add_f32_e32 v45, v79, v45
	v_mov_b32_e32 v79, 0
	s_nop 0
	v_add_f32_dpp v45, v45, v45 quad_perm:[1,0,3,2] row_mask:0xf bank_mask:0xf bound_ctrl:1
	s_nop 1
	v_add_f32_dpp v45, v45, v45 quad_perm:[2,3,0,1] row_mask:0xf bank_mask:0xf bound_ctrl:1
	s_nop 1
	v_add_f32_dpp v45, v45, v45 row_half_mirror row_mask:0xf bank_mask:0xf bound_ctrl:1
	s_nop 1
	v_add_f32_dpp v45, v45, v45 row_mirror row_mask:0xf bank_mask:0xf bound_ctrl:1
	s_nop 1
	v_mov_b32_dpp v79, v45 row_bcast:15 row_mask:0xa bank_mask:0xf bound_ctrl:1
	v_add_f32_e32 v79, v45, v79
	s_and_saveexec_b64 s[8:9], s[4:5]
	s_xor_b64 s[8:9], exec, s[8:9]
	s_cbranch_execz .LBB0_545
	v_readlane_b32 s52, v79, 63

.LBB0_549:
	s_add_i32 s49, s9, s2
	s_add_i32 s31, s8, s15
	v_mad_i64_i32 v[84:85], s[50:51], s49, v77, v[2:3]
	v_mad_i64_i32 v[86:87], s[50:51], s31, v77, v[2:3]
	global_load_dword v84, v[84:85], off
	global_load_dword v86, v[86:87], off
	s_add_i32 s49, s9, s16
	s_add_i32 s31, s8, s17
	v_mad_i64_i32 v[88:89], s[50:51], s49, v77, v[2:3]
	v_mad_i64_i32 v[90:91], s[50:51], s31, v77, v[2:3]
	global_load_dword v88, v[88:89], off
	global_load_dword v90, v[90:91], off
	s_add_i32 s49, s9, s22
	s_add_i32 s31, s8, s23
	v_mad_i64_i32 v[92:93], s[50:51], s49, v77, v[2:3]
	v_mad_i64_i32 v[94:95], s[50:51], s31, v77, v[2:3]
	global_load_dword v92, v[92:93], off
	global_load_dword v94, v[94:95], off
	s_add_i32 s49, s9, s24
	s_add_i32 s31, s8, s25
	v_mad_i64_i32 v[96:97], s[50:51], s49, v77, v[2:3]
	v_mad_i64_i32 v[98:99], s[50:51], s31, v77, v[2:3]
	global_load_dword v96, v[96:97], off
	global_load_dword v98, v[98:99], off
	s_add_i32 s49, s9, s26
	s_add_i32 s31, s8, s27
	v_mad_i64_i32 v[100:101], s[50:51], s49, v77, v[2:3]
	v_mad_i64_i32 v[102:103], s[50:51], s31, v77, v[2:3]
	global_load_dword v100, v[100:101], off
	global_load_dword v102, v[102:103], off
	s_add_i32 s49, s9, s33
	s_add_i32 s31, s8, s34
	v_mad_i64_i32 v[104:105], s[50:51], s49, v77, v[2:3]
	v_mad_i64_i32 v[106:107], s[50:51], s31, v77, v[2:3]
	global_load_dword v104, v[104:105], off
	global_load_dword v106, v[106:107], off
	s_add_i32 s49, s9, s35
	s_add_i32 s31, s8, s36
	v_mad_i64_i32 v[108:109], s[50:51], s49, v77, v[2:3]
	v_mad_i64_i32 v[110:111], s[50:51], s31, v77, v[2:3]
	global_load_dword v108, v[108:109], off
	global_load_dword v110, v[110:111], off
	s_add_i32 s49, s9, s37
	s_add_i32 s31, s8, s38
	v_mad_i64_i32 v[112:113], s[50:51], s49, v77, v[2:3]
	v_mad_i64_i32 v[114:115], s[50:51], s31, v77, v[2:3]
	global_load_dword v112, v[112:113], off
	global_load_dword v114, v[114:115], off
	s_waitcnt vmcnt(14)
	v_perm_b32 v29, v86, v84, s41
	v_perm_b32 v4, v86, v84, s42
	s_add_i32 s49, s9, s2
	v_lshl_add_u32 v30, s49, 1, v55
	v_add_u32_e32 v5, 0x1000, v30
	ds_write2_b32 v5, v29, v4 offset1:129
	s_waitcnt vmcnt(12)
	v_perm_b32 v29, v90, v88, s41
	v_perm_b32 v4, v90, v88, s42
	s_add_i32 s49, s9, s16
	v_lshl_add_u32 v30, s49, 1, v55
	v_add_u32_e32 v5, 0x1000, v30
	ds_write2_b32 v5, v29, v4 offset1:129
	s_waitcnt vmcnt(10)
	v_perm_b32 v29, v94, v92, s41
	v_perm_b32 v4, v94, v92, s42
	s_add_i32 s49, s9, s22
	v_lshl_add_u32 v30, s49, 1, v55
	v_add_u32_e32 v5, 0x1000, v30
	ds_write2_b32 v5, v29, v4 offset1:129
	s_waitcnt vmcnt(8)
	v_perm_b32 v29, v98, v96, s41
	v_perm_b32 v4, v98, v96, s42
	s_add_i32 s49, s9, s24
	v_lshl_add_u32 v30, s49, 1, v55
	v_add_u32_e32 v5, 0x1000, v30
	ds_write2_b32 v5, v29, v4 offset1:129
	s_waitcnt vmcnt(6)
	v_perm_b32 v29, v102, v100, s41
	v_perm_b32 v4, v102, v100, s42
	s_add_i32 s49, s9, s26
	v_lshl_add_u32 v30, s49, 1, v55
	v_add_u32_e32 v5, 0x1000, v30
	ds_write2_b32 v5, v29, v4 offset1:129
	s_waitcnt vmcnt(4)
	v_perm_b32 v29, v106, v104, s41
	v_perm_b32 v4, v106, v104, s42
	s_add_i32 s49, s9, s33
	v_lshl_add_u32 v30, s49, 1, v55
	v_add_u32_e32 v5, 0x1000, v30
	ds_write2_b32 v5, v29, v4 offset1:129
	s_waitcnt vmcnt(2)
	v_perm_b32 v29, v110, v108, s41
	v_perm_b32 v4, v110, v108, s42
	s_add_i32 s49, s9, s35
	v_lshl_add_u32 v30, s49, 1, v55
	v_add_u32_e32 v5, 0x1000, v30
	ds_write2_b32 v5, v29, v4 offset1:129
	s_waitcnt vmcnt(0)
	v_perm_b32 v29, v114, v112, s41
	v_perm_b32 v4, v114, v112, s42
	s_add_i32 s49, s9, s37
	v_lshl_add_u32 v30, s49, 1, v55
	v_add_u32_e32 v5, 0x1000, v30
	ds_write2_b32 v5, v29, v4 offset1:129
	s_add_i32 s9, s9, 16
	s_add_i32 s8, s8, 16
	s_add_i32 s30, s30, -16
	s_cmp_lg_u32 s30, 0
	s_cbranch_scc1 .LBB0_549
	s_add_i32 s8, s48, s47
	s_ashr_i32 s9, s8, 31
	s_lshl_b32 s30, s46, 5
	s_lshl_b64 s[8:9], s[8:9], 20
	s_and_b32 s30, s30, 0x1e00
	s_or_b32 s8, s8, s30
	v_lshl_add_u64 v[2:3], v[26:27], 0, s[8:9]
	s_mov_b64 s[8:9], 0
	v_mov_b32_e32 v4, v57
	s_waitcnt lgkmcnt(0)
	s_barrier

.LBB0_560:
	v_lshl_add_u64 v[50:51], s[94:95], 0, v[64:65]
	v_add_co_u32_e32 v52, vcc, 0x26400000, v50
	s_waitcnt vmcnt(1)
	v_and_b32_e32 v75, 0xffff0000, v42
	v_addc_co_u32_e32 v53, vcc, 0, v51, vcc
	global_load_dwordx4 v[88:91], v[52:53], off
	v_add_co_u32_e32 v136, vcc, 0x26407000, v50
	s_nop 1
	v_addc_co_u32_e32 v137, vcc, 0, v51, vcc
	global_load_dwordx4 v[124:127], v[136:137], off
	v_add_co_u32_e32 v136, vcc, 0x2640e000, v50
	s_nop 1
	v_addc_co_u32_e32 v137, vcc, 0, v51, vcc
	global_load_dwordx4 v[128:131], v[136:137], off
	v_add_co_u32_e32 v136, vcc, 0x26415000, v50
	s_nop 1
	v_addc_co_u32_e32 v137, vcc, 0, v51, vcc
	global_load_dwordx4 v[132:135], v[136:137], off
	v_lshlrev_b32_e32 v74, 16, v42
	v_and_b32_e32 v77, 0xffff0000, v43
	v_lshlrev_b32_e32 v76, 16, v43
	v_and_b32_e32 v79, 0xffff0000, v44
	v_lshlrev_b32_e32 v78, 16, v44
	v_and_b32_e32 v81, 0xffff0000, v45
	v_lshlrev_b32_e32 v80, 16, v45
	v_and_b32_e32 v53, 0xffff0000, v38
	v_lshlrev_b32_e32 v52, 16, v38
	s_waitcnt vmcnt(4)
	v_and_b32_e32 v87, 0xffff0000, v46
	v_lshlrev_b32_e32 v86, 16, v46
	v_and_b32_e32 v67, 0xffff0000, v39
	v_lshlrev_b32_e32 v66, 16, v39
	v_and_b32_e32 v85, 0xffff0000, v47
	v_lshlrev_b32_e32 v84, 16, v47
	v_and_b32_e32 v39, 0xffff0000, v40
	v_lshlrev_b32_e32 v38, 16, v40
	v_and_b32_e32 v83, 0xffff0000, v48
	v_lshlrev_b32_e32 v82, 16, v48
	v_and_b32_e32 v43, 0xffff0000, v41
	v_lshlrev_b32_e32 v42, 16, v41
	v_and_b32_e32 v47, 0xffff0000, v49
	v_lshlrev_b32_e32 v46, 16, v49
	v_pk_mul_f32 v[40:41], v[14:15], v[74:75]
	v_pk_mul_f32 v[44:45], v[16:17], v[76:77]
	v_pk_mul_f32 v[48:49], v[18:19], v[78:79]
	v_pk_mul_f32 v[68:69], v[20:21], v[80:81]
	v_pk_fma_f32 v[40:41], v[10:11], v[52:53], v[40:41]
	v_pk_fma_f32 v[44:45], v[12:13], v[66:67], v[44:45]
	v_pk_fma_f32 v[38:39], v[6:7], v[38:39], v[48:49]
	v_pk_fma_f32 v[42:43], v[8:9], v[42:43], v[68:69]
	v_pk_fma_f32 v[40:41], v[22:23], v[86:87], v[40:41]
	v_pk_fma_f32 v[44:45], v[24:25], v[84:85], v[44:45]
	v_pk_fma_f32 v[38:39], v[26:27], v[82:83], v[38:39]
	v_pk_fma_f32 v[42:43], v[28:29], v[46:47], v[42:43]
	v_cndmask_b32_e64 v2, 0, 1, s[20:21]
	v_cmp_ne_u32_e64 s[4:5], 1, v2
	s_andn2_b64 vcc, exec, s[20:21]
	s_waitcnt vmcnt(3)
	v_and_b32_e32 v53, 0xffff0000, v88
	v_lshlrev_b32_e32 v52, 16, v88
	v_and_b32_e32 v69, 0xffff0000, v89
	v_lshlrev_b32_e32 v68, 16, v89
	v_and_b32_e32 v71, 0xffff0000, v90
	v_lshlrev_b32_e32 v70, 16, v90
	v_and_b32_e32 v73, 0xffff0000, v91
	v_lshlrev_b32_e32 v72, 16, v91
	v_pk_fma_f32 v[40:41], v[30:31], v[52:53], v[40:41]
	v_pk_fma_f32 v[44:45], v[32:33], v[68:69], v[44:45]
	v_pk_fma_f32 v[48:49], v[34:35], v[70:71], v[38:39]
	v_pk_fma_f32 v[42:43], v[36:37], v[72:73], v[42:43]
	v_mul_f32_e32 v2, 0xbfb8aa3b, v40
	v_mul_f32_e32 v38, 0xbfb8aa3b, v41
	v_mul_f32_e32 v39, 0xbfb8aa3b, v44
	v_mul_f32_e32 v66, 0xbfb8aa3b, v45
	v_mul_f32_e32 v67, 0xbfb8aa3b, v48
	v_mul_f32_e32 v88, 0xbfb8aa3b, v49
	v_mul_f32_e32 v89, 0xbfb8aa3b, v42
	v_mul_f32_e32 v90, 0xbfb8aa3b, v43
	v_exp_f32_e32 v2, v2
	v_exp_f32_e32 v38, v38
	v_exp_f32_e32 v39, v39
	v_exp_f32_e32 v66, v66
	v_exp_f32_e32 v67, v67
	v_exp_f32_e32 v88, v88
	v_exp_f32_e32 v89, v89
	v_exp_f32_e32 v90, v90
	v_add_f32_e32 v2, 1.0, v2
	v_add_f32_e32 v91, 1.0, v38
	v_add_f32_e32 v92, 1.0, v39
	v_add_f32_e32 v93, 1.0, v66
	v_add_f32_e32 v94, 1.0, v67
	v_add_f32_e32 v95, 1.0, v88
	v_add_f32_e32 v97, 1.0, v89
	v_add_f32_e32 v98, 1.0, v90
	v_rcp_f32_e32 v38, v2
	v_rcp_f32_e32 v39, v91
	v_rcp_f32_e32 v66, v92
	v_rcp_f32_e32 v67, v93
	v_rcp_f32_e32 v88, v94
	v_rcp_f32_e32 v89, v95
	v_rcp_f32_e32 v90, v97
	v_rcp_f32_e32 v91, v98
	v_pk_mul_f32 v[38:39], v[40:41], v[38:39]
	v_pk_mul_f32 v[44:45], v[44:45], v[66:67]
	v_pk_mul_f32 v[40:41], v[48:49], v[88:89]
	v_pk_mul_f32 v[42:43], v[42:43], v[90:91]
	s_cbranch_vccnz .LBB0_562
	v_pk_mul_f32 v[48:49], v[38:39], v[38:39]
	v_pk_mul_f32 v[66:67], v[44:45], v[44:45]
	v_add_f32_e32 v2, v48, v49
	v_add_f32_e32 v2, v66, v2
	v_pk_mul_f32 v[88:89], v[40:41], v[40:41]
	v_add_f32_e32 v2, v67, v2
	v_add_f32_e32 v2, v88, v2
	v_pk_mul_f32 v[90:91], v[42:43], v[42:43]
	v_add_f32_e32 v2, v89, v2
	v_add_f32_e32 v2, v90, v2
	v_add_f32_e32 v2, v91, v2
	s_nop 1
	v_add_f32_dpp v2, v2, v2 quad_perm:[1,0,3,2] row_mask:0xf bank_mask:0xf bound_ctrl:1
	s_nop 1
	v_add_f32_dpp v2, v2, v2 quad_perm:[2,3,0,1] row_mask:0xf bank_mask:0xf bound_ctrl:1
	s_nop 1
	v_add_f32_dpp v2, v2, v2 row_half_mirror row_mask:0xf bank_mask:0xf bound_ctrl:1
	s_nop 1
	v_add_f32_dpp v2, v2, v2 row_mirror row_mask:0xf bank_mask:0xf bound_ctrl:1
	v_add_f32_e32 v2, 0x358637bd, v2
	v_rsq_f32_e32 v2, v2
	s_nop 0
	v_pk_mul_f32 v[38:39], v[38:39], v[2:3] op_sel_hi:[1,0]
	v_pk_mul_f32 v[44:45], v[44:45], v[2:3] op_sel_hi:[1,0]
	v_pk_mul_f32 v[40:41], v[40:41], v[2:3] op_sel_hi:[1,0]
	v_pk_mul_f32 v[42:43], v[42:43], v[2:3] op_sel_hi:[1,0]

.LBB0_568:
	s_nop 1
	v_add_co_u32_e32 v38, vcc, 0x26407000, v50
	v_pk_mul_f32 v[42:43], v[14:15], v[86:87]
	s_nop 0
	v_addc_co_u32_e32 v39, vcc, 0, v51, vcc
	s_waitcnt vmcnt(2)
	v_mov_b32_e32 v38, v124
	v_mov_b32_e32 v39, v125
	v_mov_b32_e32 v40, v126
	v_mov_b32_e32 v41, v127
	v_pk_fma_f32 v[42:43], v[10:11], v[74:75], v[42:43]
	s_and_b64 vcc, exec, s[4:5]
	v_pk_fma_f32 v[42:43], v[22:23], v[52:53], v[42:43]
	s_nop 0
	v_and_b32_e32 v75, 0xffff0000, v38
	v_lshlrev_b32_e32 v74, 16, v38
	v_pk_fma_f32 v[42:43], v[30:31], v[74:75], v[42:43]
	s_nop 0
	v_mul_f32_e32 v2, 0xbfb8aa3b, v42
	v_exp_f32_e32 v2, v2
	s_nop 0
	v_add_f32_e32 v2, 1.0, v2
	v_rcp_f32_e32 v44, v2
	v_mul_f32_e32 v2, 0xbfb8aa3b, v43
	v_exp_f32_e32 v2, v2
	s_nop 0
	v_add_f32_e32 v2, 1.0, v2
	v_rcp_f32_e32 v45, v2
	s_nop 0
	v_pk_mul_f32 v[42:43], v[42:43], v[44:45]
	v_pk_mul_f32 v[44:45], v[16:17], v[84:85]
	s_nop 0
	v_pk_fma_f32 v[44:45], v[12:13], v[76:77], v[44:45]
	v_and_b32_e32 v77, 0xffff0000, v39
	v_pk_fma_f32 v[44:45], v[24:25], v[68:69], v[44:45]
	v_lshlrev_b32_e32 v76, 16, v39
	v_pk_fma_f32 v[44:45], v[32:33], v[76:77], v[44:45]
	s_nop 0
	v_mul_f32_e32 v2, 0xbfb8aa3b, v44
	v_exp_f32_e32 v2, v2
	s_nop 0
	v_add_f32_e32 v2, 1.0, v2
	v_rcp_f32_e32 v48, v2
	v_mul_f32_e32 v2, 0xbfb8aa3b, v45
	v_exp_f32_e32 v2, v2
	s_nop 0
	v_add_f32_e32 v2, 1.0, v2
	v_rcp_f32_e32 v49, v2
	s_nop 0
	v_pk_mul_f32 v[44:45], v[44:45], v[48:49]
	v_pk_mul_f32 v[48:49], v[18:19], v[82:83]
	s_nop 0
	v_pk_fma_f32 v[48:49], v[6:7], v[78:79], v[48:49]
	v_and_b32_e32 v79, 0xffff0000, v40
	v_pk_fma_f32 v[48:49], v[26:27], v[70:71], v[48:49]
	v_lshlrev_b32_e32 v78, 16, v40
	v_pk_fma_f32 v[48:49], v[34:35], v[78:79], v[48:49]
	s_nop 0
	v_mul_f32_e32 v2, 0xbfb8aa3b, v48
	v_exp_f32_e32 v2, v2
	s_nop 0
	v_add_f32_e32 v2, 1.0, v2
	v_rcp_f32_e32 v88, v2
	v_mul_f32_e32 v2, 0xbfb8aa3b, v49
	v_exp_f32_e32 v2, v2
	s_nop 0
	v_add_f32_e32 v2, 1.0, v2
	v_rcp_f32_e32 v89, v2
	s_nop 0
	v_pk_mul_f32 v[48:49], v[48:49], v[88:89]
	v_pk_mul_f32 v[88:89], v[20:21], v[46:47]
	s_nop 0
	v_pk_fma_f32 v[80:81], v[8:9], v[80:81], v[88:89]
	s_nop 0
	v_pk_fma_f32 v[88:89], v[28:29], v[72:73], v[80:81]
	v_and_b32_e32 v81, 0xffff0000, v41
	v_lshlrev_b32_e32 v80, 16, v41
	v_pk_fma_f32 v[88:89], v[36:37], v[80:81], v[88:89]
	s_nop 0
	v_mul_f32_e32 v2, 0xbfb8aa3b, v88
	v_exp_f32_e32 v2, v2
	s_nop 0
	v_add_f32_e32 v2, 1.0, v2
	v_rcp_f32_e32 v90, v2
	v_mul_f32_e32 v2, 0xbfb8aa3b, v89
	v_exp_f32_e32 v2, v2
	s_nop 0
	v_add_f32_e32 v2, 1.0, v2
	v_rcp_f32_e32 v91, v2
	s_nop 0
	v_pk_mul_f32 v[88:89], v[88:89], v[90:91]
	s_cbranch_vccnz .LBB0_570
	v_pk_mul_f32 v[90:91], v[42:43], v[42:43]
	v_pk_mul_f32 v[92:93], v[44:45], v[44:45]
	v_add_f32_e32 v2, v90, v91
	v_add_f32_e32 v2, v92, v2
	v_pk_mul_f32 v[94:95], v[48:49], v[48:49]
	v_add_f32_e32 v2, v93, v2
	v_add_f32_e32 v2, v94, v2
	v_pk_mul_f32 v[98:99], v[88:89], v[88:89]
	v_add_f32_e32 v2, v95, v2
	v_add_f32_e32 v2, v98, v2
	v_add_f32_e32 v2, v99, v2
	s_nop 1
	v_add_f32_dpp v2, v2, v2 quad_perm:[1,0,3,2] row_mask:0xf bank_mask:0xf bound_ctrl:1
	s_nop 1
	v_add_f32_dpp v2, v2, v2 quad_perm:[2,3,0,1] row_mask:0xf bank_mask:0xf bound_ctrl:1
	s_nop 1
	v_add_f32_dpp v2, v2, v2 row_half_mirror row_mask:0xf bank_mask:0xf bound_ctrl:1
	s_nop 1
	v_add_f32_dpp v2, v2, v2 row_mirror row_mask:0xf bank_mask:0xf bound_ctrl:1
	v_add_f32_e32 v2, 0x358637bd, v2
	v_rsq_f32_e32 v2, v2
	s_nop 0
	v_pk_mul_f32 v[42:43], v[42:43], v[2:3] op_sel_hi:[1,0]
	v_pk_mul_f32 v[44:45], v[44:45], v[2:3] op_sel_hi:[1,0]
	v_pk_mul_f32 v[48:49], v[48:49], v[2:3] op_sel_hi:[1,0]
	v_pk_mul_f32 v[88:89], v[88:89], v[2:3] op_sel_hi:[1,0]

.LBB0_576:
	s_nop 1
	v_add_co_u32_e32 v42, vcc, 0x2640e000, v50
	v_pk_mul_f32 v[48:49], v[14:15], v[52:53]
	s_nop 0
	v_addc_co_u32_e32 v43, vcc, 0, v51, vcc
	s_and_b64 vcc, exec, s[20:21]
	s_cbranch_vccz .Lpg_ns2
	s_waitcnt vmcnt(3)
	s_branch .Lpg_j2
.Lpg_ns2:
	s_waitcnt vmcnt(1)
.Lpg_j2:
	v_mov_b32_e32 v42, v128
	v_mov_b32_e32 v43, v129
	v_mov_b32_e32 v44, v130
	v_mov_b32_e32 v45, v131
	v_pk_fma_f32 v[48:49], v[10:11], v[86:87], v[48:49]
	s_and_b64 vcc, exec, s[4:5]
	v_pk_fma_f32 v[48:49], v[22:23], v[74:75], v[48:49]
	s_nop 0
	v_and_b32_e32 v87, 0xffff0000, v42
	v_lshlrev_b32_e32 v86, 16, v42
	v_pk_fma_f32 v[48:49], v[30:31], v[86:87], v[48:49]
	s_nop 0
	v_mul_f32_e32 v2, 0xbfb8aa3b, v48
	v_exp_f32_e32 v2, v2
	s_nop 0
	v_add_f32_e32 v2, 1.0, v2
	v_rcp_f32_e32 v88, v2
	v_mul_f32_e32 v2, 0xbfb8aa3b, v49
	v_exp_f32_e32 v2, v2
	s_nop 0
	v_add_f32_e32 v2, 1.0, v2
	v_rcp_f32_e32 v89, v2
	s_nop 0
	v_pk_mul_f32 v[48:49], v[48:49], v[88:89]
	v_pk_mul_f32 v[88:89], v[16:17], v[68:69]
	s_nop 0
	v_pk_fma_f32 v[84:85], v[12:13], v[84:85], v[88:89]
	s_nop 0
	v_pk_fma_f32 v[88:89], v[24:25], v[76:77], v[84:85]
	v_and_b32_e32 v85, 0xffff0000, v43
	v_lshlrev_b32_e32 v84, 16, v43
	v_pk_fma_f32 v[88:89], v[32:33], v[84:85], v[88:89]
	s_nop 0
	v_mul_f32_e32 v2, 0xbfb8aa3b, v88
	v_exp_f32_e32 v2, v2
	s_nop 0
	v_add_f32_e32 v2, 1.0, v2
	v_rcp_f32_e32 v90, v2
	v_mul_f32_e32 v2, 0xbfb8aa3b, v89
	v_exp_f32_e32 v2, v2
	s_nop 0
	v_add_f32_e32 v2, 1.0, v2
	v_rcp_f32_e32 v91, v2
	s_nop 0
	v_pk_mul_f32 v[90:91], v[88:89], v[90:91]
	v_pk_mul_f32 v[88:89], v[18:19], v[70:71]
	s_nop 0
	v_pk_fma_f32 v[82:83], v[6:7], v[82:83], v[88:89]
	s_nop 0
	v_pk_fma_f32 v[88:89], v[26:27], v[78:79], v[82:83]
	v_and_b32_e32 v83, 0xffff0000, v44
	v_lshlrev_b32_e32 v82, 16, v44
	v_pk_fma_f32 v[88:89], v[34:35], v[82:83], v[88:89]
	s_nop 0
	v_mul_f32_e32 v2, 0xbfb8aa3b, v88
	v_exp_f32_e32 v2, v2
	s_nop 0
	v_add_f32_e32 v2, 1.0, v2
	v_rcp_f32_e32 v92, v2
	v_mul_f32_e32 v2, 0xbfb8aa3b, v89
	v_exp_f32_e32 v2, v2
	s_nop 0
	v_add_f32_e32 v2, 1.0, v2
	v_rcp_f32_e32 v93, v2
	s_nop 0
	v_pk_mul_f32 v[92:93], v[88:89], v[92:93]
	v_pk_mul_f32 v[88:89], v[20:21], v[72:73]
	s_nop 0
	v_pk_fma_f32 v[46:47], v[8:9], v[46:47], v[88:89]
	v_and_b32_e32 v89, 0xffff0000, v45
	v_pk_fma_f32 v[46:47], v[28:29], v[80:81], v[46:47]
	v_lshlrev_b32_e32 v88, 16, v45
	v_pk_fma_f32 v[46:47], v[36:37], v[88:89], v[46:47]
	s_nop 0
	v_mul_f32_e32 v2, 0xbfb8aa3b, v46
	v_exp_f32_e32 v2, v2
	s_nop 0
	v_add_f32_e32 v2, 1.0, v2
	v_rcp_f32_e32 v94, v2
	v_mul_f32_e32 v2, 0xbfb8aa3b, v47
	v_exp_f32_e32 v2, v2
	s_nop 0
	v_add_f32_e32 v2, 1.0, v2
	v_rcp_f32_e32 v95, v2
	s_nop 0
	v_pk_mul_f32 v[94:95], v[46:47], v[94:95]
	s_cbranch_vccnz .LBB0_578
	v_pk_mul_f32 v[46:47], v[48:49], v[48:49]
	v_pk_mul_f32 v[98:99], v[90:91], v[90:91]
	v_add_f32_e32 v2, v46, v47
	v_add_f32_e32 v2, v98, v2
	v_pk_mul_f32 v[100:101], v[92:93], v[92:93]
	v_add_f32_e32 v2, v99, v2
	v_add_f32_e32 v2, v100, v2
	v_pk_mul_f32 v[102:103], v[94:95], v[94:95]
	v_add_f32_e32 v2, v101, v2
	v_add_f32_e32 v2, v102, v2
	v_add_f32_e32 v2, v103, v2
	s_nop 1
	v_add_f32_dpp v2, v2, v2 quad_perm:[1,0,3,2] row_mask:0xf bank_mask:0xf bound_ctrl:1
	s_nop 1
	v_add_f32_dpp v2, v2, v2 quad_perm:[2,3,0,1] row_mask:0xf bank_mask:0xf bound_ctrl:1
	s_nop 1
	v_add_f32_dpp v2, v2, v2 row_half_mirror row_mask:0xf bank_mask:0xf bound_ctrl:1
	s_nop 1
	v_add_f32_dpp v2, v2, v2 row_mirror row_mask:0xf bank_mask:0xf bound_ctrl:1
	v_add_f32_e32 v2, 0x358637bd, v2
	v_rsq_f32_e32 v2, v2
	s_nop 0
	v_pk_mul_f32 v[48:49], v[48:49], v[2:3] op_sel_hi:[1,0]
	v_pk_mul_f32 v[90:91], v[90:91], v[2:3] op_sel_hi:[1,0]
	v_pk_mul_f32 v[92:93], v[92:93], v[2:3] op_sel_hi:[1,0]
	v_pk_mul_f32 v[94:95], v[94:95], v[2:3] op_sel_hi:[1,0]

.LBB0_584:
	s_nop 1
	v_add_co_u32_e32 v46, vcc, 0x26415000, v50
	s_nop 1
	v_addc_co_u32_e32 v47, vcc, 0, v51, vcc
	s_and_b64 vcc, exec, s[20:21]
	s_cbranch_vccz .Lpg_ns3
	s_waitcnt vmcnt(3)
	s_branch .Lpg_j3

.Lpg_j3:
	v_mov_b32_e32 v46, v132
	v_mov_b32_e32 v47, v133
	v_mov_b32_e32 v48, v134
	v_mov_b32_e32 v49, v135
	v_pk_mul_f32 v[50:51], v[14:15], v[74:75]
	v_pk_mul_f32 v[74:75], v[16:17], v[76:77]
	v_pk_mul_f32 v[76:77], v[18:19], v[78:79]
	v_pk_mul_f32 v[78:79], v[20:21], v[80:81]
	v_pk_fma_f32 v[50:51], v[10:11], v[52:53], v[50:51]
	v_pk_fma_f32 v[52:53], v[12:13], v[68:69], v[74:75]
	v_pk_fma_f32 v[68:69], v[6:7], v[70:71], v[76:77]
	v_pk_fma_f32 v[70:71], v[8:9], v[72:73], v[78:79]
	v_pk_fma_f32 v[50:51], v[22:23], v[86:87], v[50:51]
	v_pk_fma_f32 v[52:53], v[24:25], v[84:85], v[52:53]
	v_pk_fma_f32 v[68:69], v[26:27], v[82:83], v[68:69]
	v_pk_fma_f32 v[70:71], v[28:29], v[88:89], v[70:71]
	s_and_b64 vcc, exec, s[4:5]
	s_nop 0
	v_and_b32_e32 v73, 0xffff0000, v46
	v_lshlrev_b32_e32 v72, 16, v46
	v_and_b32_e32 v75, 0xffff0000, v47
	v_lshlrev_b32_e32 v74, 16, v47
	v_and_b32_e32 v77, 0xffff0000, v48
	v_lshlrev_b32_e32 v76, 16, v48
	v_and_b32_e32 v79, 0xffff0000, v49
	v_lshlrev_b32_e32 v78, 16, v49
	v_pk_fma_f32 v[50:51], v[30:31], v[72:73], v[50:51]
	v_pk_fma_f32 v[52:53], v[32:33], v[74:75], v[52:53]
	v_pk_fma_f32 v[68:69], v[34:35], v[76:77], v[68:69]
	v_pk_fma_f32 v[72:73], v[36:37], v[78:79], v[70:71]
	v_mul_f32_e32 v2, 0xbfb8aa3b, v50
	v_mul_f32_e32 v70, 0xbfb8aa3b, v51
	v_mul_f32_e32 v71, 0xbfb8aa3b, v52
	v_mul_f32_e32 v74, 0xbfb8aa3b, v53
	v_mul_f32_e32 v75, 0xbfb8aa3b, v68
	v_mul_f32_e32 v76, 0xbfb8aa3b, v69
	v_mul_f32_e32 v77, 0xbfb8aa3b, v72
	v_mul_f32_e32 v78, 0xbfb8aa3b, v73
	v_exp_f32_e32 v2, v2
	v_exp_f32_e32 v70, v70
	v_exp_f32_e32 v71, v71
	v_exp_f32_e32 v74, v74
	v_exp_f32_e32 v75, v75
	v_exp_f32_e32 v76, v76
	v_exp_f32_e32 v77, v77
	v_exp_f32_e32 v78, v78
	v_add_f32_e32 v2, 1.0, v2
	v_add_f32_e32 v79, 1.0, v70
	v_add_f32_e32 v80, 1.0, v71
	v_add_f32_e32 v81, 1.0, v74
	v_add_f32_e32 v82, 1.0, v75
	v_add_f32_e32 v83, 1.0, v76
	v_add_f32_e32 v84, 1.0, v77
	v_add_f32_e32 v85, 1.0, v78
	v_rcp_f32_e32 v70, v2
	v_rcp_f32_e32 v71, v79
	v_rcp_f32_e32 v74, v80
	v_rcp_f32_e32 v75, v81
	v_rcp_f32_e32 v76, v82
	v_rcp_f32_e32 v77, v83
	v_rcp_f32_e32 v78, v84
	v_rcp_f32_e32 v79, v85
	v_pk_mul_f32 v[50:51], v[50:51], v[70:71]
	v_pk_mul_f32 v[70:71], v[52:53], v[74:75]
	v_pk_mul_f32 v[52:53], v[68:69], v[76:77]
	v_pk_mul_f32 v[68:69], v[72:73], v[78:79]
	s_cbranch_vccnz .LBB0_586
	v_pk_mul_f32 v[72:73], v[50:51], v[50:51]
	v_pk_mul_f32 v[74:75], v[70:71], v[70:71]
	v_add_f32_e32 v2, v72, v73
	v_add_f32_e32 v2, v74, v2
	v_pk_mul_f32 v[76:77], v[52:53], v[52:53]
	v_add_f32_e32 v2, v75, v2
	v_add_f32_e32 v2, v76, v2
	v_pk_mul_f32 v[78:79], v[68:69], v[68:69]
	v_add_f32_e32 v2, v77, v2
	v_add_f32_e32 v2, v78, v2
	v_add_f32_e32 v2, v79, v2
	s_nop 1
	v_add_f32_dpp v2, v2, v2 quad_perm:[1,0,3,2] row_mask:0xf bank_mask:0xf bound_ctrl:1
	s_nop 1
	v_add_f32_dpp v2, v2, v2 quad_perm:[2,3,0,1] row_mask:0xf bank_mask:0xf bound_ctrl:1
	s_nop 1
	v_add_f32_dpp v2, v2, v2 row_half_mirror row_mask:0xf bank_mask:0xf bound_ctrl:1
	s_nop 1
	v_add_f32_dpp v2, v2, v2 row_mirror row_mask:0xf bank_mask:0xf bound_ctrl:1
	v_add_f32_e32 v2, 0x358637bd, v2
	v_rsq_f32_e32 v2, v2
	s_nop 0
	v_pk_mul_f32 v[50:51], v[50:51], v[2:3] op_sel_hi:[1,0]
	v_pk_mul_f32 v[70:71], v[70:71], v[2:3] op_sel_hi:[1,0]
	v_pk_mul_f32 v[52:53], v[52:53], v[2:3] op_sel_hi:[1,0]
	v_pk_mul_f32 v[68:69], v[68:69], v[2:3] op_sel_hi:[1,0]

.LBB0_855:
	s_waitcnt lgkmcnt(0)
	s_barrier
	ds_read2_b32 v[148:149], v181 offset1:66
	s_waitcnt vmcnt(29)
	v_lshlrev_b32_e32 v220, 16, v227
	v_and_b32_e32 v221, 0xffff0000, v227
	s_lshl_b64 s[40:41], s[40:41], 13
	v_add_u32_e32 v150, 0x400, v181
	s_waitcnt lgkmcnt(0)
	v_lshlrev_b32_e32 v160, 16, v148
	v_and_b32_e32 v161, 0xffff0000, v148
	v_pk_mul_f32 v[222:223], v[160:161], v[160:161]
	v_lshlrev_b32_e32 v162, 16, v149
	v_add_f32_e32 v222, v222, v223
	v_mov_b32_e32 v223, 0
	v_and_b32_e32 v163, 0xffff0000, v149
	v_add_f32_dpp v222, v222, v222 quad_perm:[1,0,3,2] row_mask:0xf bank_mask:0xf bound_ctrl:1
	ds_read2_b32 v[148:149], v181 offset0:132 offset1:198
	s_add_i32 s29, s29, 2
	v_add_f32_dpp v222, v222, v222 quad_perm:[2,3,0,1] row_mask:0xf bank_mask:0xf bound_ctrl:1
	v_lshl_add_u64 v[132:133], v[132:133], 0, s[26:27]
	v_lshl_add_u64 v[134:135], v[134:135], 0, s[26:27]
	v_add_f32_dpp v222, v222, v222 row_half_mirror row_mask:0xf bank_mask:0xf bound_ctrl:1
	s_waitcnt lgkmcnt(0)
	v_lshlrev_b32_e32 v158, 16, v148
	v_and_b32_e32 v159, 0xffff0000, v148
	v_add_f32_dpp v222, v222, v222 row_mirror row_mask:0xf bank_mask:0xf bound_ctrl:1
	v_lshlrev_b32_e32 v156, 16, v149
	v_and_b32_e32 v157, 0xffff0000, v149
	v_mov_b32_dpp v223, v222 row_bcast:15 row_mask:0xa bank_mask:0xf bound_ctrl:1
	v_add_f32_e32 v222, v222, v223
	v_mul_f32_e32 v223, 0xbfb8aa3b, v220
	v_readlane_b32 s43, v222, 63
	v_readlane_b32 s42, v222, 31
	v_exp_f32_e32 v223, v223
	v_mov_b32_e32 v222, s43
	v_add_f32_e32 v222, s42, v222
	v_fmamk_f32 v222, v222, 0x3c000000, v187
	v_rsq_f32_e32 v222, v222
	v_add_f32_e32 v223, 1.0, v223
	v_rcp_f32_e32 v228, v223
	ds_read2_b32 v[148:149], v150 offset0:8 offset1:74
	v_pk_mul_f32 v[160:161], v[222:223], v[160:161] op_sel_hi:[0,1]
	v_mul_f32_e32 v222, 0xbfb8aa3b, v221
	v_exp_f32_e32 v222, v222
	v_pk_mul_f32 v[160:161], v[114:115], v[160:161]
	s_waitcnt lgkmcnt(0)
	v_lshlrev_b32_e32 v154, 16, v148
	v_and_b32_e32 v155, 0xffff0000, v148
	v_add_f32_e32 v222, 1.0, v222
	v_rcp_f32_e32 v229, v222
	v_lshlrev_b32_e32 v152, 16, v149
	v_and_b32_e32 v153, 0xffff0000, v149
	ds_read2_b32 v[148:149], v150 offset0:140 offset1:206
	v_pk_mul_f32 v[220:221], v[228:229], v[220:221]
	v_lshl_add_u64 v[144:145], v[144:145], 0, s[26:27]
	v_pk_mul_f32 v[160:161], v[220:221], v[160:161]
	v_lshl_add_u64 v[146:147], v[146:147], 0, s[26:27]
	v_cvt_pk_bf16_f32 v220, v160, v161
	v_lshl_add_u64 v[160:161], v[120:121], 0, s[40:41]
	global_store_dword v[160:161], v220, off
	v_pk_mul_f32 v[220:221], v[162:163], v[162:163]
	s_waitcnt vmcnt(29)
	v_lshlrev_b32_e32 v160, 16, v226
	v_add_f32_e32 v220, v220, v221
	v_mov_b32_e32 v221, 0
	v_and_b32_e32 v161, 0xffff0000, v226
	v_add_f32_dpp v220, v220, v220 quad_perm:[1,0,3,2] row_mask:0xf bank_mask:0xf bound_ctrl:1
	s_waitcnt lgkmcnt(0)
	v_lshlrev_b32_e32 v150, 16, v148
	v_and_b32_e32 v151, 0xffff0000, v148
	v_add_f32_dpp v220, v220, v220 quad_perm:[2,3,0,1] row_mask:0xf bank_mask:0xf bound_ctrl:1
	v_lshlrev_b32_e32 v148, 16, v149
	v_and_b32_e32 v149, 0xffff0000, v149
	v_add_f32_dpp v220, v220, v220 row_half_mirror row_mask:0xf bank_mask:0xf bound_ctrl:1
	s_nop 1
	v_add_f32_dpp v220, v220, v220 row_mirror row_mask:0xf bank_mask:0xf bound_ctrl:1
	s_nop 1
	v_mov_b32_dpp v221, v220 row_bcast:15 row_mask:0xa bank_mask:0xf bound_ctrl:1
	v_add_f32_e32 v220, v220, v221
	v_mul_f32_e32 v221, 0xbfb8aa3b, v160
	v_readlane_b32 s41, v220, 63
	v_readlane_b32 s40, v220, 31
	v_exp_f32_e32 v221, v221
	v_mov_b32_e32 v220, s41
	v_add_f32_e32 v220, s40, v220
	v_fmamk_f32 v220, v220, 0x3c000000, v187
	v_rsq_f32_e32 v220, v220
	v_add_f32_e32 v221, 1.0, v221
	v_rcp_f32_e32 v222, v221
	s_lshl_b64 s[40:41], s[72:73], 13
	v_pk_mul_f32 v[162:163], v[220:221], v[162:163] op_sel_hi:[0,1]
	v_mul_f32_e32 v220, 0xbfb8aa3b, v161
	v_exp_f32_e32 v220, v220
	v_pk_mul_f32 v[162:163], v[114:115], v[162:163]
	v_add_f32_e32 v220, 1.0, v220
	v_rcp_f32_e32 v223, v220
	s_nop 0
	v_pk_mul_f32 v[160:161], v[222:223], v[160:161]
	s_nop 0
	v_pk_mul_f32 v[160:161], v[160:161], v[162:163]
	s_nop 0
	v_cvt_pk_bf16_f32 v162, v160, v161
	v_lshl_add_u64 v[160:161], v[120:121], 0, s[40:41]
	global_store_dword v[160:161], v162, off
	v_pk_mul_f32 v[162:163], v[158:159], v[158:159]
	s_waitcnt vmcnt(29)
	v_lshlrev_b32_e32 v160, 16, v225
	v_add_f32_e32 v162, v162, v163
	v_mov_b32_e32 v163, 0
	v_and_b32_e32 v161, 0xffff0000, v225
	v_add_f32_dpp v162, v162, v162 quad_perm:[1,0,3,2] row_mask:0xf bank_mask:0xf bound_ctrl:1
	s_nop 1
	v_add_f32_dpp v162, v162, v162 quad_perm:[2,3,0,1] row_mask:0xf bank_mask:0xf bound_ctrl:1
	s_nop 1
	v_add_f32_dpp v162, v162, v162 row_half_mirror row_mask:0xf bank_mask:0xf bound_ctrl:1
	s_nop 1
	v_add_f32_dpp v162, v162, v162 row_mirror row_mask:0xf bank_mask:0xf bound_ctrl:1
	s_nop 1
	v_mov_b32_dpp v163, v162 row_bcast:15 row_mask:0xa bank_mask:0xf bound_ctrl:1
	v_add_f32_e32 v162, v162, v163
	v_mul_f32_e32 v163, 0xbfb8aa3b, v160
	v_readlane_b32 s41, v162, 63
	v_readlane_b32 s40, v162, 31
	v_exp_f32_e32 v163, v163
	v_mov_b32_e32 v162, s41
	v_add_f32_e32 v162, s40, v162
	v_fmamk_f32 v162, v162, 0x3c000000, v187
	v_rsq_f32_e32 v162, v162
	v_add_f32_e32 v163, 1.0, v163
	v_rcp_f32_e32 v220, v163
	s_lshl_b64 s[40:41], s[70:71], 13
	v_pk_mul_f32 v[158:159], v[162:163], v[158:159] op_sel_hi:[0,1]
	v_mul_f32_e32 v162, 0xbfb8aa3b, v161
	v_exp_f32_e32 v162, v162
	v_pk_mul_f32 v[158:159], v[114:115], v[158:159]
	v_add_f32_e32 v162, 1.0, v162
	v_rcp_f32_e32 v221, v162
	s_nop 0
	v_pk_mul_f32 v[160:161], v[220:221], v[160:161]
	s_nop 0
	v_pk_mul_f32 v[158:159], v[160:161], v[158:159]
	s_nop 0
	v_cvt_pk_bf16_f32 v160, v158, v159
	v_lshl_add_u64 v[158:159], v[120:121], 0, s[40:41]
	global_store_dword v[158:159], v160, off
	v_pk_mul_f32 v[160:161], v[156:157], v[156:157]
	s_waitcnt vmcnt(29)
	v_lshlrev_b32_e32 v158, 16, v224
	v_add_f32_e32 v160, v160, v161
	v_mov_b32_e32 v161, 0
	v_and_b32_e32 v159, 0xffff0000, v224
	v_add_f32_dpp v160, v160, v160 quad_perm:[1,0,3,2] row_mask:0xf bank_mask:0xf bound_ctrl:1
	s_nop 1
	v_add_f32_dpp v160, v160, v160 quad_perm:[2,3,0,1] row_mask:0xf bank_mask:0xf bound_ctrl:1
	s_nop 1
	v_add_f32_dpp v160, v160, v160 row_half_mirror row_mask:0xf bank_mask:0xf bound_ctrl:1
	s_nop 1
	v_add_f32_dpp v160, v160, v160 row_mirror row_mask:0xf bank_mask:0xf bound_ctrl:1
	s_nop 1
	v_mov_b32_dpp v161, v160 row_bcast:15 row_mask:0xa bank_mask:0xf bound_ctrl:1
	v_add_f32_e32 v160, v160, v161
	v_mul_f32_e32 v161, 0xbfb8aa3b, v158
	v_readlane_b32 s41, v160, 63
	v_readlane_b32 s40, v160, 31
	v_exp_f32_e32 v161, v161
	v_mov_b32_e32 v160, s41
	v_add_f32_e32 v160, s40, v160
	v_fmamk_f32 v160, v160, 0x3c000000, v187
	v_rsq_f32_e32 v160, v160
	v_add_f32_e32 v161, 1.0, v161
	v_rcp_f32_e32 v162, v161
	s_lshl_b64 s[40:41], s[68:69], 13
	v_pk_mul_f32 v[156:157], v[160:161], v[156:157] op_sel_hi:[0,1]
	v_mul_f32_e32 v160, 0xbfb8aa3b, v159
	v_exp_f32_e32 v160, v160
	v_pk_mul_f32 v[156:157], v[114:115], v[156:157]
	v_add_f32_e32 v160, 1.0, v160
	v_rcp_f32_e32 v163, v160
	s_nop 0
	v_pk_mul_f32 v[158:159], v[162:163], v[158:159]
	s_nop 0
	v_pk_mul_f32 v[156:157], v[158:159], v[156:157]
	s_nop 0
	v_cvt_pk_bf16_f32 v158, v156, v157
	v_lshl_add_u64 v[156:157], v[120:121], 0, s[40:41]
	global_store_dword v[156:157], v158, off
	v_pk_mul_f32 v[158:159], v[154:155], v[154:155]
	s_waitcnt vmcnt(29)
	v_lshlrev_b32_e32 v156, 16, v175
	v_add_f32_e32 v158, v158, v159
	v_mov_b32_e32 v159, 0
	v_and_b32_e32 v157, 0xffff0000, v175
	v_add_f32_dpp v158, v158, v158 quad_perm:[1,0,3,2] row_mask:0xf bank_mask:0xf bound_ctrl:1
	s_nop 1
	v_add_f32_dpp v158, v158, v158 quad_perm:[2,3,0,1] row_mask:0xf bank_mask:0xf bound_ctrl:1
	s_nop 1
	v_add_f32_dpp v158, v158, v158 row_half_mirror row_mask:0xf bank_mask:0xf bound_ctrl:1
	s_nop 1
	v_add_f32_dpp v158, v158, v158 row_mirror row_mask:0xf bank_mask:0xf bound_ctrl:1
	s_nop 1
	v_mov_b32_dpp v159, v158 row_bcast:15 row_mask:0xa bank_mask:0xf bound_ctrl:1
	v_add_f32_e32 v158, v158, v159
	v_mul_f32_e32 v159, 0xbfb8aa3b, v156
	v_readlane_b32 s41, v158, 63
	v_readlane_b32 s40, v158, 31
	v_exp_f32_e32 v159, v159
	v_mov_b32_e32 v158, s41
	v_add_f32_e32 v158, s40, v158
	v_fmamk_f32 v158, v158, 0x3c000000, v187
	v_rsq_f32_e32 v158, v158
	v_add_f32_e32 v159, 1.0, v159
	v_rcp_f32_e32 v160, v159
	s_lshl_b64 s[40:41], s[66:67], 13
	v_pk_mul_f32 v[154:155], v[158:159], v[154:155] op_sel_hi:[0,1]
	v_mul_f32_e32 v158, 0xbfb8aa3b, v157
	v_exp_f32_e32 v158, v158
	v_pk_mul_f32 v[154:155], v[114:115], v[154:155]
	v_add_f32_e32 v158, 1.0, v158
	v_rcp_f32_e32 v161, v158
	s_nop 0
	v_pk_mul_f32 v[156:157], v[160:161], v[156:157]
	s_nop 0
	v_pk_mul_f32 v[154:155], v[156:157], v[154:155]
	s_nop 0
	v_cvt_pk_bf16_f32 v156, v154, v155
	v_lshl_add_u64 v[154:155], v[120:121], 0, s[40:41]
	global_store_dword v[154:155], v156, off
	v_pk_mul_f32 v[156:157], v[152:153], v[152:153]
	s_waitcnt vmcnt(29)
	v_lshlrev_b32_e32 v154, 16, v174
	v_add_f32_e32 v156, v156, v157
	v_mov_b32_e32 v157, 0
	v_and_b32_e32 v155, 0xffff0000, v174
	v_add_f32_dpp v156, v156, v156 quad_perm:[1,0,3,2] row_mask:0xf bank_mask:0xf bound_ctrl:1
	s_nop 1
	v_add_f32_dpp v156, v156, v156 quad_perm:[2,3,0,1] row_mask:0xf bank_mask:0xf bound_ctrl:1
	s_nop 1
	v_add_f32_dpp v156, v156, v156 row_half_mirror row_mask:0xf bank_mask:0xf bound_ctrl:1
	s_nop 1
	v_add_f32_dpp v156, v156, v156 row_mirror row_mask:0xf bank_mask:0xf bound_ctrl:1
	s_nop 1
	v_mov_b32_dpp v157, v156 row_bcast:15 row_mask:0xa bank_mask:0xf bound_ctrl:1
	v_add_f32_e32 v156, v156, v157
	v_mul_f32_e32 v157, 0xbfb8aa3b, v154
	v_readlane_b32 s41, v156, 63
	v_readlane_b32 s40, v156, 31
	v_exp_f32_e32 v157, v157
	v_mov_b32_e32 v156, s41
	v_add_f32_e32 v156, s40, v156
	v_fmamk_f32 v156, v156, 0x3c000000, v187
	v_rsq_f32_e32 v156, v156
	v_add_f32_e32 v157, 1.0, v157
	v_rcp_f32_e32 v158, v157
	s_lshl_b64 s[40:41], s[64:65], 13
	v_pk_mul_f32 v[152:153], v[156:157], v[152:153] op_sel_hi:[0,1]
	v_mul_f32_e32 v156, 0xbfb8aa3b, v155
	v_exp_f32_e32 v156, v156
	v_pk_mul_f32 v[152:153], v[114:115], v[152:153]
	v_add_f32_e32 v156, 1.0, v156
	v_rcp_f32_e32 v159, v156
	s_nop 0
	v_pk_mul_f32 v[154:155], v[158:159], v[154:155]
	s_nop 0
	v_pk_mul_f32 v[152:153], v[154:155], v[152:153]
	s_nop 0
	v_cvt_pk_bf16_f32 v154, v152, v153
	v_lshl_add_u64 v[152:153], v[120:121], 0, s[40:41]
	global_store_dword v[152:153], v154, off
	v_pk_mul_f32 v[154:155], v[150:151], v[150:151]
	s_waitcnt vmcnt(29)
	v_lshlrev_b32_e32 v152, 16, v173
	v_add_f32_e32 v154, v154, v155
	v_mov_b32_e32 v155, 0
	v_and_b32_e32 v153, 0xffff0000, v173
	v_add_f32_dpp v154, v154, v154 quad_perm:[1,0,3,2] row_mask:0xf bank_mask:0xf bound_ctrl:1
	s_waitcnt vmcnt(27)
	v_and_b32_e32 v173, 0xffff0000, v171
	v_add_f32_dpp v154, v154, v154 quad_perm:[2,3,0,1] row_mask:0xf bank_mask:0xf bound_ctrl:1
	s_nop 1
	v_add_f32_dpp v154, v154, v154 row_half_mirror row_mask:0xf bank_mask:0xf bound_ctrl:1
	s_nop 1
	v_add_f32_dpp v154, v154, v154 row_mirror row_mask:0xf bank_mask:0xf bound_ctrl:1
	s_nop 1
	v_mov_b32_dpp v155, v154 row_bcast:15 row_mask:0xa bank_mask:0xf bound_ctrl:1
	v_add_f32_e32 v154, v154, v155
	v_mul_f32_e32 v155, 0xbfb8aa3b, v152
	v_readlane_b32 s41, v154, 63
	v_readlane_b32 s40, v154, 31
	v_exp_f32_e32 v155, v155
	v_mov_b32_e32 v154, s41
	v_add_f32_e32 v154, s40, v154
	v_fmamk_f32 v154, v154, 0x3c000000, v187
	v_rsq_f32_e32 v154, v154
	v_add_f32_e32 v155, 1.0, v155
	v_rcp_f32_e32 v156, v155
	s_lshl_b64 s[40:41], s[62:63], 13
	v_pk_mul_f32 v[150:151], v[154:155], v[150:151] op_sel_hi:[0,1]
	v_mul_f32_e32 v154, 0xbfb8aa3b, v153
	v_exp_f32_e32 v154, v154
	v_pk_mul_f32 v[150:151], v[114:115], v[150:151]
	v_add_f32_e32 v154, 1.0, v154
	v_rcp_f32_e32 v157, v154
	s_nop 0
	v_pk_mul_f32 v[152:153], v[156:157], v[152:153]
	s_nop 0
	v_pk_mul_f32 v[150:151], v[152:153], v[150:151]
	s_nop 0
	v_cvt_pk_bf16_f32 v152, v150, v151
	v_lshl_add_u64 v[150:151], v[120:121], 0, s[40:41]
	global_store_dword v[150:151], v152, off
	v_pk_mul_f32 v[152:153], v[148:149], v[148:149]
	v_lshlrev_b32_e32 v150, 16, v172
	v_add_f32_e32 v152, v152, v153
	v_mov_b32_e32 v153, 0
	v_and_b32_e32 v151, 0xffff0000, v172
	v_add_f32_dpp v152, v152, v152 quad_perm:[1,0,3,2] row_mask:0xf bank_mask:0xf bound_ctrl:1
	v_lshlrev_b32_e32 v172, 16, v171
	s_nop 0
	v_add_f32_dpp v152, v152, v152 quad_perm:[2,3,0,1] row_mask:0xf bank_mask:0xf bound_ctrl:1
	s_nop 1
	v_add_f32_dpp v152, v152, v152 row_half_mirror row_mask:0xf bank_mask:0xf bound_ctrl:1
	s_nop 1
	v_add_f32_dpp v152, v152, v152 row_mirror row_mask:0xf bank_mask:0xf bound_ctrl:1
	s_nop 1
	v_mov_b32_dpp v153, v152 row_bcast:15 row_mask:0xa bank_mask:0xf bound_ctrl:1
	v_add_f32_e32 v152, v152, v153
	v_mul_f32_e32 v153, 0xbfb8aa3b, v150
	v_readlane_b32 s41, v152, 63
	v_readlane_b32 s40, v152, 31
	v_exp_f32_e32 v153, v153
	v_mov_b32_e32 v152, s41
	v_add_f32_e32 v152, s40, v152
	v_fmamk_f32 v152, v152, 0x3c000000, v187
	v_rsq_f32_e32 v152, v152
	v_add_f32_e32 v153, 1.0, v153
	v_rcp_f32_e32 v154, v153
	s_lshl_b64 s[40:41], s[60:61], 13
	v_pk_mul_f32 v[148:149], v[152:153], v[148:149] op_sel_hi:[0,1]
	v_mul_f32_e32 v152, 0xbfb8aa3b, v151
	v_exp_f32_e32 v152, v152
	v_pk_mul_f32 v[148:149], v[114:115], v[148:149]
	v_add_f32_e32 v152, 1.0, v152
	v_rcp_f32_e32 v155, v152
	s_nop 0
	v_pk_mul_f32 v[150:151], v[154:155], v[150:151]
	s_nop 0
	v_pk_mul_f32 v[148:149], v[150:151], v[148:149]
	s_nop 0
	v_cvt_pk_bf16_f32 v150, v148, v149
	v_lshl_add_u64 v[148:149], v[120:121], 0, s[40:41]
	global_store_dword v[148:149], v150, off
	v_add_u32_e32 v150, 0x800, v181
	ds_read2_b32 v[148:149], v150 offset0:16 offset1:82
	s_waitcnt lgkmcnt(0)
	v_lshlrev_b32_e32 v160, 16, v148
	v_and_b32_e32 v161, 0xffff0000, v148
	v_pk_mul_f32 v[174:175], v[160:161], v[160:161]
	v_lshlrev_b32_e32 v162, 16, v149
	v_add_f32_e32 v171, v174, v175
	v_mov_b32_e32 v174, 0
	v_and_b32_e32 v163, 0xffff0000, v149
	v_add_f32_dpp v171, v171, v171 quad_perm:[1,0,3,2] row_mask:0xf bank_mask:0xf bound_ctrl:1
	ds_read2_b32 v[148:149], v150 offset0:148 offset1:214
	v_add_u32_e32 v150, 0xc00, v181
	v_add_f32_dpp v171, v171, v171 quad_perm:[2,3,0,1] row_mask:0xf bank_mask:0xf bound_ctrl:1
	s_waitcnt lgkmcnt(0)
	v_lshlrev_b32_e32 v158, 16, v148
	v_add_f32_dpp v171, v171, v171 row_half_mirror row_mask:0xf bank_mask:0xf bound_ctrl:1
	v_and_b32_e32 v159, 0xffff0000, v148
	v_lshlrev_b32_e32 v156, 16, v149
	v_add_f32_dpp v171, v171, v171 row_mirror row_mask:0xf bank_mask:0xf bound_ctrl:1
	v_and_b32_e32 v157, 0xffff0000, v149
	ds_read2_b32 v[148:149], v150 offset0:24 offset1:90
	v_mov_b32_dpp v174, v171 row_bcast:15 row_mask:0xa bank_mask:0xf bound_ctrl:1
	v_add_f32_e32 v171, v171, v174
	s_waitcnt lgkmcnt(0)
	v_lshlrev_b32_e32 v154, 16, v148
	v_readlane_b32 s41, v171, 63
	v_readlane_b32 s40, v171, 31
	v_and_b32_e32 v155, 0xffff0000, v148
	v_mov_b32_e32 v171, s41
	v_add_f32_e32 v171, s40, v171
	v_fmamk_f32 v171, v171, 0x3c000000, v187
	v_rsq_f32_e32 v174, v171
	v_mul_f32_e32 v171, 0xbfb8aa3b, v172
	v_exp_f32_e32 v171, v171
	s_lshl_b64 s[40:41], s[58:59], 13
	v_pk_mul_f32 v[160:161], v[174:175], v[160:161] op_sel_hi:[0,1]
	v_pk_mul_f32 v[160:161], v[114:115], v[160:161]
	v_add_f32_e32 v171, 1.0, v171
	v_rcp_f32_e32 v220, v171
	v_mul_f32_e32 v171, 0xbfb8aa3b, v173
	v_exp_f32_e32 v171, v171
	v_lshlrev_b32_e32 v152, 16, v149
	v_and_b32_e32 v153, 0xffff0000, v149
	ds_read2_b32 v[148:149], v150 offset0:156 offset1:222
	v_add_f32_e32 v171, 1.0, v171
	v_rcp_f32_e32 v221, v171
	s_waitcnt lgkmcnt(0)
	v_lshlrev_b32_e32 v150, 16, v148
	v_pk_mul_f32 v[172:173], v[220:221], v[172:173]
	v_and_b32_e32 v151, 0xffff0000, v148
	v_pk_mul_f32 v[160:161], v[172:173], v[160:161]
	v_lshlrev_b32_e32 v148, 16, v149
	v_cvt_pk_bf16_f32 v171, v160, v161
	v_lshl_add_u64 v[160:161], v[120:121], 0, s[40:41]
	global_store_dword v[160:161], v171, off
	s_waitcnt vmcnt(29)
	v_lshlrev_b32_e32 v160, 16, v170
	v_and_b32_e32 v161, 0xffff0000, v170
	v_pk_mul_f32 v[170:171], v[162:163], v[162:163]
	v_and_b32_e32 v149, 0xffff0000, v149
	v_add_f32_e32 v170, v170, v171
	v_mov_b32_e32 v171, 0
	s_nop 0
	v_add_f32_dpp v170, v170, v170 quad_perm:[1,0,3,2] row_mask:0xf bank_mask:0xf bound_ctrl:1
	s_nop 1
	v_add_f32_dpp v170, v170, v170 quad_perm:[2,3,0,1] row_mask:0xf bank_mask:0xf bound_ctrl:1
	s_nop 1
	v_add_f32_dpp v170, v170, v170 row_half_mirror row_mask:0xf bank_mask:0xf bound_ctrl:1
	s_nop 1
	v_add_f32_dpp v170, v170, v170 row_mirror row_mask:0xf bank_mask:0xf bound_ctrl:1
	s_nop 1
	v_mov_b32_dpp v171, v170 row_bcast:15 row_mask:0xa bank_mask:0xf bound_ctrl:1
	v_add_f32_e32 v170, v170, v171
	v_mul_f32_e32 v171, 0xbfb8aa3b, v160
	v_readlane_b32 s41, v170, 63
	v_readlane_b32 s40, v170, 31
	v_exp_f32_e32 v171, v171
	v_mov_b32_e32 v170, s41
	v_add_f32_e32 v170, s40, v170
	v_fmamk_f32 v170, v170, 0x3c000000, v187
	v_rsq_f32_e32 v170, v170
	v_add_f32_e32 v171, 1.0, v171
	v_rcp_f32_e32 v172, v171
	s_lshl_b64 s[40:41], s[56:57], 13
	v_pk_mul_f32 v[162:163], v[170:171], v[162:163] op_sel_hi:[0,1]
	v_mul_f32_e32 v170, 0xbfb8aa3b, v161
	v_exp_f32_e32 v170, v170
	v_pk_mul_f32 v[162:163], v[114:115], v[162:163]
	v_add_f32_e32 v170, 1.0, v170
	v_rcp_f32_e32 v173, v170
	s_nop 0
	v_pk_mul_f32 v[160:161], v[172:173], v[160:161]
	s_nop 0
	v_pk_mul_f32 v[160:161], v[160:161], v[162:163]
	s_nop 0
	v_cvt_pk_bf16_f32 v162, v160, v161
	v_lshl_add_u64 v[160:161], v[120:121], 0, s[40:41]
	global_store_dword v[160:161], v162, off
	v_pk_mul_f32 v[162:163], v[158:159], v[158:159]
	s_waitcnt vmcnt(29)
	v_lshlrev_b32_e32 v160, 16, v169
	v_add_f32_e32 v162, v162, v163
	v_mov_b32_e32 v163, 0
	v_and_b32_e32 v161, 0xffff0000, v169
	v_add_f32_dpp v162, v162, v162 quad_perm:[1,0,3,2] row_mask:0xf bank_mask:0xf bound_ctrl:1
	s_nop 1
	v_add_f32_dpp v162, v162, v162 quad_perm:[2,3,0,1] row_mask:0xf bank_mask:0xf bound_ctrl:1
	s_nop 1
	v_add_f32_dpp v162, v162, v162 row_half_mirror row_mask:0xf bank_mask:0xf bound_ctrl:1
	s_nop 1
	v_add_f32_dpp v162, v162, v162 row_mirror row_mask:0xf bank_mask:0xf bound_ctrl:1
	s_nop 1
	v_mov_b32_dpp v163, v162 row_bcast:15 row_mask:0xa bank_mask:0xf bound_ctrl:1
	v_add_f32_e32 v162, v162, v163
	v_mul_f32_e32 v163, 0xbfb8aa3b, v160
	v_readlane_b32 s41, v162, 63
	v_readlane_b32 s40, v162, 31
	v_exp_f32_e32 v163, v163
	v_mov_b32_e32 v162, s41
	v_add_f32_e32 v162, s40, v162
	v_fmamk_f32 v162, v162, 0x3c000000, v187
	v_rsq_f32_e32 v162, v162
	v_add_f32_e32 v163, 1.0, v163
	v_rcp_f32_e32 v170, v163
	s_lshl_b64 s[40:41], s[54:55], 13
	v_pk_mul_f32 v[158:159], v[162:163], v[158:159] op_sel_hi:[0,1]
	v_mul_f32_e32 v162, 0xbfb8aa3b, v161
	v_exp_f32_e32 v162, v162
	v_pk_mul_f32 v[158:159], v[114:115], v[158:159]
	v_add_f32_e32 v162, 1.0, v162
	v_rcp_f32_e32 v171, v162
	s_nop 0
	v_pk_mul_f32 v[160:161], v[170:171], v[160:161]
	s_nop 0
	v_pk_mul_f32 v[158:159], v[160:161], v[158:159]
	s_nop 0
	v_cvt_pk_bf16_f32 v160, v158, v159
	v_lshl_add_u64 v[158:159], v[120:121], 0, s[40:41]
	global_store_dword v[158:159], v160, off
	v_pk_mul_f32 v[160:161], v[156:157], v[156:157]
	s_waitcnt vmcnt(29)
	v_lshlrev_b32_e32 v158, 16, v168
	v_add_f32_e32 v160, v160, v161
	v_mov_b32_e32 v161, 0
	v_and_b32_e32 v159, 0xffff0000, v168
	v_add_f32_dpp v160, v160, v160 quad_perm:[1,0,3,2] row_mask:0xf bank_mask:0xf bound_ctrl:1
	s_nop 1
	v_add_f32_dpp v160, v160, v160 quad_perm:[2,3,0,1] row_mask:0xf bank_mask:0xf bound_ctrl:1
	s_nop 1
	v_add_f32_dpp v160, v160, v160 row_half_mirror row_mask:0xf bank_mask:0xf bound_ctrl:1
	s_nop 1
	v_add_f32_dpp v160, v160, v160 row_mirror row_mask:0xf bank_mask:0xf bound_ctrl:1
	s_nop 1
	v_mov_b32_dpp v161, v160 row_bcast:15 row_mask:0xa bank_mask:0xf bound_ctrl:1
	v_add_f32_e32 v160, v160, v161
	v_mul_f32_e32 v161, 0xbfb8aa3b, v158
	v_readlane_b32 s41, v160, 63
	v_readlane_b32 s40, v160, 31
	v_exp_f32_e32 v161, v161
	v_mov_b32_e32 v160, s41
	v_add_f32_e32 v160, s40, v160
	v_fmamk_f32 v160, v160, 0x3c000000, v187
	v_rsq_f32_e32 v160, v160
	v_add_f32_e32 v161, 1.0, v161
	v_rcp_f32_e32 v162, v161
	s_lshl_b64 s[40:41], s[52:53], 13
	v_pk_mul_f32 v[156:157], v[160:161], v[156:157] op_sel_hi:[0,1]
	v_mul_f32_e32 v160, 0xbfb8aa3b, v159
	v_exp_f32_e32 v160, v160
	v_pk_mul_f32 v[156:157], v[114:115], v[156:157]
	v_add_f32_e32 v160, 1.0, v160
	v_rcp_f32_e32 v163, v160
	s_nop 0
	v_pk_mul_f32 v[158:159], v[162:163], v[158:159]
	s_nop 0
	v_pk_mul_f32 v[156:157], v[158:159], v[156:157]
	s_nop 0
	v_cvt_pk_bf16_f32 v158, v156, v157
	v_lshl_add_u64 v[156:157], v[120:121], 0, s[40:41]
	global_store_dword v[156:157], v158, off
	v_pk_mul_f32 v[158:159], v[154:155], v[154:155]
	s_waitcnt vmcnt(29)
	v_lshlrev_b32_e32 v156, 16, v167
	v_add_f32_e32 v158, v158, v159
	v_mov_b32_e32 v159, 0
	v_and_b32_e32 v157, 0xffff0000, v167
	v_add_f32_dpp v158, v158, v158 quad_perm:[1,0,3,2] row_mask:0xf bank_mask:0xf bound_ctrl:1
	s_nop 1
	v_add_f32_dpp v158, v158, v158 quad_perm:[2,3,0,1] row_mask:0xf bank_mask:0xf bound_ctrl:1
	s_nop 1
	v_add_f32_dpp v158, v158, v158 row_half_mirror row_mask:0xf bank_mask:0xf bound_ctrl:1
	s_nop 1
	v_add_f32_dpp v158, v158, v158 row_mirror row_mask:0xf bank_mask:0xf bound_ctrl:1
	s_nop 1
	v_mov_b32_dpp v159, v158 row_bcast:15 row_mask:0xa bank_mask:0xf bound_ctrl:1
	v_add_f32_e32 v158, v158, v159
	v_mul_f32_e32 v159, 0xbfb8aa3b, v156
	v_readlane_b32 s41, v158, 63
	v_readlane_b32 s40, v158, 31
	v_exp_f32_e32 v159, v159
	v_mov_b32_e32 v158, s41
	v_add_f32_e32 v158, s40, v158
	v_fmamk_f32 v158, v158, 0x3c000000, v187
	v_rsq_f32_e32 v158, v158
	v_add_f32_e32 v159, 1.0, v159
	v_rcp_f32_e32 v160, v159
	s_lshl_b64 s[40:41], s[50:51], 13
	v_pk_mul_f32 v[154:155], v[158:159], v[154:155] op_sel_hi:[0,1]
	v_mul_f32_e32 v158, 0xbfb8aa3b, v157
	v_exp_f32_e32 v158, v158
	v_pk_mul_f32 v[154:155], v[114:115], v[154:155]
	v_add_f32_e32 v158, 1.0, v158
	v_rcp_f32_e32 v161, v158
	s_nop 0
	v_pk_mul_f32 v[156:157], v[160:161], v[156:157]
	s_nop 0
	v_pk_mul_f32 v[154:155], v[156:157], v[154:155]
	s_nop 0
	v_cvt_pk_bf16_f32 v156, v154, v155
	v_lshl_add_u64 v[154:155], v[120:121], 0, s[40:41]
	global_store_dword v[154:155], v156, off
	v_pk_mul_f32 v[156:157], v[152:153], v[152:153]
	s_waitcnt vmcnt(29)
	v_lshlrev_b32_e32 v154, 16, v166
	v_add_f32_e32 v156, v156, v157
	v_mov_b32_e32 v157, 0
	v_and_b32_e32 v155, 0xffff0000, v166
	v_add_f32_dpp v156, v156, v156 quad_perm:[1,0,3,2] row_mask:0xf bank_mask:0xf bound_ctrl:1
	s_nop 1
	v_add_f32_dpp v156, v156, v156 quad_perm:[2,3,0,1] row_mask:0xf bank_mask:0xf bound_ctrl:1
	s_nop 1
	v_add_f32_dpp v156, v156, v156 row_half_mirror row_mask:0xf bank_mask:0xf bound_ctrl:1
	s_nop 1
	v_add_f32_dpp v156, v156, v156 row_mirror row_mask:0xf bank_mask:0xf bound_ctrl:1
	s_nop 1
	v_mov_b32_dpp v157, v156 row_bcast:15 row_mask:0xa bank_mask:0xf bound_ctrl:1
	v_add_f32_e32 v156, v156, v157
	v_mul_f32_e32 v157, 0xbfb8aa3b, v154
	v_readlane_b32 s41, v156, 63
	v_readlane_b32 s40, v156, 31
	v_exp_f32_e32 v157, v157
	v_mov_b32_e32 v156, s41
	v_add_f32_e32 v156, s40, v156
	v_fmamk_f32 v156, v156, 0x3c000000, v187
	v_rsq_f32_e32 v156, v156
	v_add_f32_e32 v157, 1.0, v157
	v_rcp_f32_e32 v158, v157
	s_lshl_b64 s[40:41], s[48:49], 13
	v_pk_mul_f32 v[152:153], v[156:157], v[152:153] op_sel_hi:[0,1]
	v_mul_f32_e32 v156, 0xbfb8aa3b, v155
	v_exp_f32_e32 v156, v156
	v_pk_mul_f32 v[152:153], v[114:115], v[152:153]
	v_add_f32_e32 v156, 1.0, v156
	v_rcp_f32_e32 v159, v156
	s_nop 0
	v_pk_mul_f32 v[154:155], v[158:159], v[154:155]
	s_nop 0
	v_pk_mul_f32 v[152:153], v[154:155], v[152:153]
	s_nop 0
	v_cvt_pk_bf16_f32 v154, v152, v153
	v_lshl_add_u64 v[152:153], v[120:121], 0, s[40:41]
	global_store_dword v[152:153], v154, off
	v_pk_mul_f32 v[154:155], v[150:151], v[150:151]
	s_waitcnt vmcnt(29)
	v_lshlrev_b32_e32 v152, 16, v165
	v_add_f32_e32 v154, v154, v155
	v_mov_b32_e32 v155, 0
	v_and_b32_e32 v153, 0xffff0000, v165
	v_add_f32_dpp v154, v154, v154 quad_perm:[1,0,3,2] row_mask:0xf bank_mask:0xf bound_ctrl:1
	s_nop 1
	v_add_f32_dpp v154, v154, v154 quad_perm:[2,3,0,1] row_mask:0xf bank_mask:0xf bound_ctrl:1
	s_nop 1
	v_add_f32_dpp v154, v154, v154 row_half_mirror row_mask:0xf bank_mask:0xf bound_ctrl:1
	s_nop 1
	v_add_f32_dpp v154, v154, v154 row_mirror row_mask:0xf bank_mask:0xf bound_ctrl:1
	s_nop 1
	v_mov_b32_dpp v155, v154 row_bcast:15 row_mask:0xa bank_mask:0xf bound_ctrl:1
	v_add_f32_e32 v154, v154, v155
	v_mul_f32_e32 v155, 0xbfb8aa3b, v152
	v_readlane_b32 s41, v154, 63
	v_readlane_b32 s40, v154, 31
	v_exp_f32_e32 v155, v155
	v_mov_b32_e32 v154, s41
	v_add_f32_e32 v154, s40, v154
	v_fmamk_f32 v154, v154, 0x3c000000, v187
	v_rsq_f32_e32 v154, v154
	v_add_f32_e32 v155, 1.0, v155
	v_rcp_f32_e32 v156, v155
	s_lshl_b64 s[40:41], s[46:47], 13
	v_pk_mul_f32 v[150:151], v[154:155], v[150:151] op_sel_hi:[0,1]
	v_mul_f32_e32 v154, 0xbfb8aa3b, v153
	v_exp_f32_e32 v154, v154
	v_pk_mul_f32 v[150:151], v[114:115], v[150:151]
	v_add_f32_e32 v154, 1.0, v154
	v_rcp_f32_e32 v157, v154
	s_nop 0
	v_pk_mul_f32 v[152:153], v[156:157], v[152:153]
	s_nop 0
	v_pk_mul_f32 v[150:151], v[152:153], v[150:151]
	s_nop 0
	v_cvt_pk_bf16_f32 v152, v150, v151
	v_lshl_add_u64 v[150:151], v[120:121], 0, s[40:41]
	global_store_dword v[150:151], v152, off
	v_pk_mul_f32 v[152:153], v[148:149], v[148:149]
	s_waitcnt vmcnt(29)
	v_lshlrev_b32_e32 v150, 16, v164
	v_add_f32_e32 v152, v152, v153
	v_mov_b32_e32 v153, 0
	v_and_b32_e32 v151, 0xffff0000, v164
	v_add_f32_dpp v152, v152, v152 quad_perm:[1,0,3,2] row_mask:0xf bank_mask:0xf bound_ctrl:1
	s_nop 1
	v_add_f32_dpp v152, v152, v152 quad_perm:[2,3,0,1] row_mask:0xf bank_mask:0xf bound_ctrl:1
	s_nop 1
	v_add_f32_dpp v152, v152, v152 row_half_mirror row_mask:0xf bank_mask:0xf bound_ctrl:1
	s_nop 1
	v_add_f32_dpp v152, v152, v152 row_mirror row_mask:0xf bank_mask:0xf bound_ctrl:1
	s_nop 1
	v_mov_b32_dpp v153, v152 row_bcast:15 row_mask:0xa bank_mask:0xf bound_ctrl:1
	v_add_f32_e32 v152, v152, v153
	v_mul_f32_e32 v153, 0xbfb8aa3b, v150
	v_readlane_b32 s41, v152, 63
	v_readlane_b32 s40, v152, 31
	v_exp_f32_e32 v153, v153
	v_mov_b32_e32 v152, s41
	v_add_f32_e32 v152, s40, v152
	v_fmamk_f32 v152, v152, 0x3c000000, v187
	v_rsq_f32_e32 v152, v152
	v_add_f32_e32 v153, 1.0, v153
	v_rcp_f32_e32 v154, v153
	s_lshl_b64 s[40:41], s[44:45], 13
	v_pk_mul_f32 v[148:149], v[152:153], v[148:149] op_sel_hi:[0,1]
	v_mul_f32_e32 v152, 0xbfb8aa3b, v151
	v_exp_f32_e32 v152, v152
	s_add_u32 s30, s30, 0x8000
	v_pk_mul_f32 v[148:149], v[114:115], v[148:149]
	s_addc_u32 s31, s31, 0
	v_add_f32_e32 v152, 1.0, v152
	v_rcp_f32_e32 v155, v152
	s_add_u32 s36, s36, 0x200
	s_addc_u32 s37, s37, 0
	s_addk_i32 s80, 0x80
	v_pk_mul_f32 v[150:151], v[154:155], v[150:151]
	s_and_b64 vcc, exec, s[38:39]
	v_pk_mul_f32 v[148:149], v[150:151], v[148:149]
	s_nop 0
	v_cvt_pk_bf16_f32 v150, v148, v149
	v_lshl_add_u64 v[148:149], v[120:121], 0, s[40:41]
	global_store_dword v[148:149], v150, off
	s_cbranch_vccnz .LBB0_839

.LBB0_860:
	v_add3_u32 v164, v190, v191, s89
	s_waitcnt vmcnt(43)
	ds_write2_b64 v164, v[42:43], v[44:45] offset1:1
	v_add_u32_e32 v164, v214, v191
	s_waitcnt vmcnt(42)
	ds_write2_b64 v164, v[50:51], v[52:53] offset1:1
	v_add3_u32 v164, v190, v194, s89
	s_waitcnt vmcnt(41)
	ds_write2_b64 v164, v[58:59], v[60:61] offset1:1
	v_add_u32_e32 v164, v214, v194
	s_waitcnt vmcnt(40)
	ds_write2_b64 v164, v[62:63], v[64:65] offset1:1
	v_add3_u32 v164, v190, v197, s89
	s_waitcnt vmcnt(39)
	ds_write2_b64 v164, v[74:75], v[76:77] offset1:1
	v_add_u32_e32 v164, v214, v197
	s_waitcnt vmcnt(38)
	ds_write2_b64 v164, v[78:79], v[80:81] offset1:1
	v_add3_u32 v164, v190, v200, s89
	s_waitcnt vmcnt(37)
	ds_write2_b64 v164, v[82:83], v[84:85] offset1:1
	v_add_u32_e32 v164, v214, v200
	s_waitcnt vmcnt(36)
	ds_write2_b64 v164, v[86:87], v[88:89] offset1:1
	v_add_u32_e32 v164, v215, v203
	s_waitcnt vmcnt(35)
	ds_write2_b64 v164, v[90:91], v[92:93] offset1:1
	v_add_u32_e32 v164, v215, v205
	s_waitcnt vmcnt(34)
	ds_write2_b64 v164, v[94:95], v[96:97] offset1:1
	v_add_u32_e32 v164, v216, v203
	s_waitcnt vmcnt(33)
	ds_write2_b64 v164, v[98:99], v[100:101] offset1:1
	v_add_u32_e32 v164, v216, v205
	s_waitcnt vmcnt(32)
	ds_write2_b64 v164, v[102:103], v[104:105] offset1:1
	v_add_u32_e32 v164, v216, v209
	s_ashr_i32 s75, s74, 31
	s_ashr_i32 s73, s72, 31
	s_ashr_i32 s71, s70, 31
	s_ashr_i32 s69, s68, 31
	s_ashr_i32 s67, s66, 31
	s_ashr_i32 s65, s64, 31
	s_ashr_i32 s63, s62, 31
	s_ashr_i32 s61, s60, 31
	s_ashr_i32 s59, s58, 31
	s_ashr_i32 s57, s56, 31
	s_ashr_i32 s55, s54, 31
	s_ashr_i32 s53, s52, 31
	s_ashr_i32 s51, s50, 31
	s_ashr_i32 s49, s48, 31
	s_ashr_i32 s47, s46, 31
	s_ashr_i32 s45, s44, 31
	s_waitcnt vmcnt(31)
	ds_write2_b64 v164, v[106:107], v[108:109] offset1:1
	v_add_u32_e32 v164, v216, v211
	s_waitcnt vmcnt(30)
	ds_write2_b64 v164, v[110:111], v[112:113] offset1:1
	s_and_saveexec_b64 s[76:77], s[0:1]
	s_cbranch_execz .LBB0_862
	v_mul_f32_e32 v165, 0x3fb8aa3b, v219
	v_sub_f32_e32 v164, v185, v219
	v_exp_f32_e32 v165, v165
	v_mul_f32_e32 v164, 0x3fb8aa3b, v164
	v_exp_f32_e32 v164, v164
	v_mul_f32_e32 v165, 0x3db504f3, v165
	ds_write_b32 v217, v165
	ds_write_b32 v218, v164
.LBB0_862:
	s_or_b64 exec, exec, s[76:77]
	s_waitcnt lgkmcnt(0)
	s_barrier
	ds_read2_b32 v[164:165], v180 offset1:66
	s_waitcnt vmcnt(29)
	v_lshlrev_b32_e32 v244, 16, v239
	v_and_b32_e32 v245, 0xffff0000, v239
	s_lshl_b64 s[74:75], s[74:75], 13
	s_lshl_b64 s[72:73], s[72:73], 13
	s_waitcnt lgkmcnt(0)
	v_lshlrev_b32_e32 v240, 16, v164
	v_and_b32_e32 v241, 0xffff0000, v164
	v_pk_mul_f32 v[246:247], v[240:241], v[240:241]
	v_lshlrev_b32_e32 v242, 16, v165
	v_add_f32_e32 v239, v246, v247
	v_mov_b32_e32 v246, 0
	v_and_b32_e32 v243, 0xffff0000, v165
	v_add_f32_dpp v239, v239, v239 quad_perm:[1,0,3,2] row_mask:0xf bank_mask:0xf bound_ctrl:1
	ds_read2_b32 v[164:165], v180 offset0:132 offset1:198
	s_lshl_b64 s[70:71], s[70:71], 13
	v_add_f32_dpp v239, v239, v239 quad_perm:[2,3,0,1] row_mask:0xf bank_mask:0xf bound_ctrl:1
	v_add_u32_e32 v166, 0x400, v180
	s_lshl_b64 s[68:69], s[68:69], 13
	v_add_f32_dpp v239, v239, v239 row_half_mirror row_mask:0xf bank_mask:0xf bound_ctrl:1
	s_waitcnt lgkmcnt(0)
	v_lshlrev_b32_e32 v174, 16, v164
	v_and_b32_e32 v175, 0xffff0000, v164
	v_add_f32_dpp v239, v239, v239 row_mirror row_mask:0xf bank_mask:0xf bound_ctrl:1
	v_lshlrev_b32_e32 v172, 16, v165
	v_and_b32_e32 v173, 0xffff0000, v165
	v_mov_b32_dpp v246, v239 row_bcast:15 row_mask:0xa bank_mask:0xf bound_ctrl:1
	v_add_f32_e32 v239, v239, v246
	ds_read2_b32 v[164:165], v166 offset0:8 offset1:74
	v_readlane_b32 s76, v239, 63
	v_readlane_b32 s41, v239, 31
	s_lshl_b64 s[66:67], s[66:67], 13
	v_mov_b32_e32 v239, s76
	v_add_f32_e32 v239, s41, v239
	v_fmamk_f32 v239, v239, 0x3c000000, v187
	v_rsq_f32_e32 v246, v239
	v_mul_f32_e32 v239, 0xbfb8aa3b, v244
	v_exp_f32_e32 v239, v239
	s_waitcnt lgkmcnt(0)
	v_lshlrev_b32_e32 v170, 16, v164
	v_pk_mul_f32 v[240:241], v[246:247], v[240:241] op_sel_hi:[0,1]
	v_pk_mul_f32 v[240:241], v[114:115], v[240:241]
	v_add_f32_e32 v239, 1.0, v239
	v_rcp_f32_e32 v248, v239
	v_mul_f32_e32 v239, 0xbfb8aa3b, v245
	v_exp_f32_e32 v239, v239
	v_and_b32_e32 v171, 0xffff0000, v164
	v_lshlrev_b32_e32 v168, 16, v165
	v_and_b32_e32 v169, 0xffff0000, v165
	v_add_f32_e32 v239, 1.0, v239
	v_rcp_f32_e32 v249, v239
	ds_read2_b32 v[164:165], v166 offset0:140 offset1:206
	s_lshl_b64 s[64:65], s[64:65], 13
	s_lshl_b64 s[62:63], s[62:63], 13
	v_pk_mul_f32 v[244:245], v[248:249], v[244:245]
	s_lshl_b64 s[60:61], s[60:61], 13
	v_pk_mul_f32 v[240:241], v[244:245], v[240:241]
	s_waitcnt lgkmcnt(0)
	v_lshlrev_b32_e32 v166, 16, v164
	v_cvt_pk_bf16_f32 v239, v240, v241
	v_lshl_add_u64 v[240:241], v[120:121], 0, s[74:75]
	global_store_dword v[240:241], v239, off
	s_waitcnt vmcnt(29)
	v_lshlrev_b32_e32 v240, 16, v238
	v_and_b32_e32 v241, 0xffff0000, v238
	v_pk_mul_f32 v[238:239], v[242:243], v[242:243]
	v_and_b32_e32 v167, 0xffff0000, v164
	v_add_f32_e32 v238, v238, v239
	v_mov_b32_e32 v239, 0
	v_lshlrev_b32_e32 v164, 16, v165
	v_add_f32_dpp v238, v238, v238 quad_perm:[1,0,3,2] row_mask:0xf bank_mask:0xf bound_ctrl:1
	v_and_b32_e32 v165, 0xffff0000, v165
	s_lshl_b64 s[58:59], s[58:59], 13
	v_add_f32_dpp v238, v238, v238 quad_perm:[2,3,0,1] row_mask:0xf bank_mask:0xf bound_ctrl:1
	s_lshl_b64 s[56:57], s[56:57], 13
	s_lshl_b64 s[54:55], s[54:55], 13
	v_add_f32_dpp v238, v238, v238 row_half_mirror row_mask:0xf bank_mask:0xf bound_ctrl:1
	s_lshl_b64 s[52:53], s[52:53], 13
	s_lshl_b64 s[50:51], s[50:51], 13
	v_add_f32_dpp v238, v238, v238 row_mirror row_mask:0xf bank_mask:0xf bound_ctrl:1
	s_lshl_b64 s[48:49], s[48:49], 13
	s_lshl_b64 s[46:47], s[46:47], 13
	v_mov_b32_dpp v239, v238 row_bcast:15 row_mask:0xa bank_mask:0xf bound_ctrl:1
	v_add_f32_e32 v238, v238, v239
	v_mul_f32_e32 v239, 0xbfb8aa3b, v240
	v_readlane_b32 s74, v238, 63
	v_readlane_b32 s41, v238, 31
	v_exp_f32_e32 v239, v239
	v_mov_b32_e32 v238, s74
	v_add_f32_e32 v238, s41, v238
	v_fmamk_f32 v238, v238, 0x3c000000, v187
	v_rsq_f32_e32 v238, v238
	v_add_f32_e32 v239, 1.0, v239
	v_rcp_f32_e32 v244, v239
	s_lshl_b64 s[44:45], s[44:45], 13
	v_pk_mul_f32 v[238:239], v[238:239], v[242:243] op_sel_hi:[0,1]
	v_mul_f32_e32 v242, 0xbfb8aa3b, v241
	v_exp_f32_e32 v242, v242
	v_pk_mul_f32 v[238:239], v[114:115], v[238:239]
	v_add_f32_e32 v242, 1.0, v242
	v_rcp_f32_e32 v245, v242
	s_nop 0
	v_pk_mul_f32 v[240:241], v[244:245], v[240:241]
	s_nop 0
	v_pk_mul_f32 v[238:239], v[240:241], v[238:239]
	s_nop 0
	v_cvt_pk_bf16_f32 v240, v238, v239
	v_lshl_add_u64 v[238:239], v[120:121], 0, s[72:73]
	global_store_dword v[238:239], v240, off
	v_pk_mul_f32 v[240:241], v[174:175], v[174:175]
	s_waitcnt vmcnt(29)
	v_lshlrev_b32_e32 v238, 16, v237
	v_and_b32_e32 v239, 0xffff0000, v237
	v_add_f32_e32 v237, v240, v241
	v_mov_b32_e32 v240, 0
	s_nop 0
	v_add_f32_dpp v237, v237, v237 quad_perm:[1,0,3,2] row_mask:0xf bank_mask:0xf bound_ctrl:1
	s_nop 1
	v_add_f32_dpp v237, v237, v237 quad_perm:[2,3,0,1] row_mask:0xf bank_mask:0xf bound_ctrl:1
	s_nop 1
	v_add_f32_dpp v237, v237, v237 row_half_mirror row_mask:0xf bank_mask:0xf bound_ctrl:1
	s_nop 1
	v_add_f32_dpp v237, v237, v237 row_mirror row_mask:0xf bank_mask:0xf bound_ctrl:1
	s_nop 1
	v_mov_b32_dpp v240, v237 row_bcast:15 row_mask:0xa bank_mask:0xf bound_ctrl:1
	v_add_f32_e32 v237, v237, v240
	s_nop 0
	v_readlane_b32 s72, v237, 63
	v_readlane_b32 s41, v237, 31
	s_nop 0
	v_mov_b32_e32 v237, s72
	v_add_f32_e32 v237, s41, v237
	v_fmamk_f32 v237, v237, 0x3c000000, v187
	v_rsq_f32_e32 v240, v237
	v_mul_f32_e32 v237, 0xbfb8aa3b, v238
	v_exp_f32_e32 v237, v237
	s_add_i32 s72, s40, 1
	v_pk_mul_f32 v[174:175], v[240:241], v[174:175] op_sel_hi:[0,1]
	v_pk_mul_f32 v[174:175], v[114:115], v[174:175]
	v_add_f32_e32 v237, 1.0, v237
	v_rcp_f32_e32 v242, v237
	v_mul_f32_e32 v237, 0xbfb8aa3b, v239
	v_exp_f32_e32 v237, v237
	s_nop 0
	v_add_f32_e32 v237, 1.0, v237
	v_rcp_f32_e32 v243, v237
	s_nop 0
	v_pk_mul_f32 v[238:239], v[242:243], v[238:239]
	s_nop 0
	v_pk_mul_f32 v[174:175], v[238:239], v[174:175]
	s_nop 0
	v_cvt_pk_bf16_f32 v237, v174, v175
	v_lshl_add_u64 v[174:175], v[120:121], 0, s[70:71]
	global_store_dword v[174:175], v237, off
	s_waitcnt vmcnt(29)
	v_lshlrev_b32_e32 v174, 16, v236
	v_and_b32_e32 v175, 0xffff0000, v236
	v_pk_mul_f32 v[236:237], v[172:173], v[172:173]
	s_nop 0
	v_add_f32_e32 v236, v236, v237
	v_mov_b32_e32 v237, 0
	s_nop 0
	v_add_f32_dpp v236, v236, v236 quad_perm:[1,0,3,2] row_mask:0xf bank_mask:0xf bound_ctrl:1
	s_nop 1
	v_add_f32_dpp v236, v236, v236 quad_perm:[2,3,0,1] row_mask:0xf bank_mask:0xf bound_ctrl:1
	s_nop 1
	v_add_f32_dpp v236, v236, v236 row_half_mirror row_mask:0xf bank_mask:0xf bound_ctrl:1
	s_nop 1
	v_add_f32_dpp v236, v236, v236 row_mirror row_mask:0xf bank_mask:0xf bound_ctrl:1
	s_nop 1
	v_mov_b32_dpp v237, v236 row_bcast:15 row_mask:0xa bank_mask:0xf bound_ctrl:1
	v_add_f32_e32 v236, v236, v237
	v_mul_f32_e32 v237, 0xbfb8aa3b, v174
	v_readlane_b32 s70, v236, 63
	v_readlane_b32 s41, v236, 31
	v_exp_f32_e32 v237, v237
	v_mov_b32_e32 v236, s70
	v_add_f32_e32 v236, s41, v236
	v_fmamk_f32 v236, v236, 0x3c000000, v187
	v_rsq_f32_e32 v236, v236
	v_add_f32_e32 v237, 1.0, v237
	v_rcp_f32_e32 v238, v237
	s_add_i32 s70, s40, 2
	v_pk_mul_f32 v[172:173], v[236:237], v[172:173] op_sel_hi:[0,1]
	v_mul_f32_e32 v236, 0xbfb8aa3b, v175
	v_exp_f32_e32 v236, v236
	v_pk_mul_f32 v[172:173], v[114:115], v[172:173]
	v_add_f32_e32 v236, 1.0, v236
	v_rcp_f32_e32 v239, v236
	s_nop 0
	v_pk_mul_f32 v[174:175], v[238:239], v[174:175]
	s_nop 0
	v_pk_mul_f32 v[172:173], v[174:175], v[172:173]
	s_nop 0
	v_cvt_pk_bf16_f32 v174, v172, v173
	v_lshl_add_u64 v[172:173], v[120:121], 0, s[68:69]
	global_store_dword v[172:173], v174, off
	v_pk_mul_f32 v[174:175], v[170:171], v[170:171]
	s_waitcnt vmcnt(29)
	v_lshlrev_b32_e32 v172, 16, v235
	v_add_f32_e32 v174, v174, v175
	v_mov_b32_e32 v175, 0
	v_and_b32_e32 v173, 0xffff0000, v235
	v_add_f32_dpp v174, v174, v174 quad_perm:[1,0,3,2] row_mask:0xf bank_mask:0xf bound_ctrl:1
	s_nop 1
	v_add_f32_dpp v174, v174, v174 quad_perm:[2,3,0,1] row_mask:0xf bank_mask:0xf bound_ctrl:1
	s_nop 1
	v_add_f32_dpp v174, v174, v174 row_half_mirror row_mask:0xf bank_mask:0xf bound_ctrl:1
	s_nop 1
	v_add_f32_dpp v174, v174, v174 row_mirror row_mask:0xf bank_mask:0xf bound_ctrl:1
	s_nop 1
	v_mov_b32_dpp v175, v174 row_bcast:15 row_mask:0xa bank_mask:0xf bound_ctrl:1
	v_add_f32_e32 v174, v174, v175
	v_mul_f32_e32 v175, 0xbfb8aa3b, v172
	v_readlane_b32 s68, v174, 63
	v_readlane_b32 s41, v174, 31
	v_exp_f32_e32 v175, v175
	v_mov_b32_e32 v174, s68
	v_add_f32_e32 v174, s41, v174
	v_fmamk_f32 v174, v174, 0x3c000000, v187
	v_rsq_f32_e32 v174, v174
	v_add_f32_e32 v175, 1.0, v175
	v_rcp_f32_e32 v236, v175
	s_add_i32 s68, s40, 3
	v_pk_mul_f32 v[170:171], v[174:175], v[170:171] op_sel_hi:[0,1]
	v_mul_f32_e32 v174, 0xbfb8aa3b, v173
	v_exp_f32_e32 v174, v174
	v_pk_mul_f32 v[170:171], v[114:115], v[170:171]
	v_add_f32_e32 v174, 1.0, v174
	v_rcp_f32_e32 v237, v174
	s_nop 0
	v_pk_mul_f32 v[172:173], v[236:237], v[172:173]
	s_nop 0
	v_pk_mul_f32 v[170:171], v[172:173], v[170:171]
	s_waitcnt vmcnt(25)
	v_lshlrev_b32_e32 v236, 16, v231
	v_cvt_pk_bf16_f32 v172, v170, v171
	v_lshl_add_u64 v[170:171], v[120:121], 0, s[66:67]
	global_store_dword v[170:171], v172, off
	v_pk_mul_f32 v[172:173], v[168:169], v[168:169]
	v_lshlrev_b32_e32 v170, 16, v234
	v_add_f32_e32 v172, v172, v173
	v_mov_b32_e32 v173, 0
	v_and_b32_e32 v171, 0xffff0000, v234
	v_add_f32_dpp v172, v172, v172 quad_perm:[1,0,3,2] row_mask:0xf bank_mask:0xf bound_ctrl:1
	v_and_b32_e32 v237, 0xffff0000, v231
	s_nop 0
	v_add_f32_dpp v172, v172, v172 quad_perm:[2,3,0,1] row_mask:0xf bank_mask:0xf bound_ctrl:1
	s_nop 1
	v_add_f32_dpp v172, v172, v172 row_half_mirror row_mask:0xf bank_mask:0xf bound_ctrl:1
	s_nop 1
	v_add_f32_dpp v172, v172, v172 row_mirror row_mask:0xf bank_mask:0xf bound_ctrl:1
	s_nop 1
	v_mov_b32_dpp v173, v172 row_bcast:15 row_mask:0xa bank_mask:0xf bound_ctrl:1
	v_add_f32_e32 v172, v172, v173
	v_mul_f32_e32 v173, 0xbfb8aa3b, v170
	v_readlane_b32 s66, v172, 63
	v_readlane_b32 s41, v172, 31
	v_exp_f32_e32 v173, v173
	v_mov_b32_e32 v172, s66
	v_add_f32_e32 v172, s41, v172
	v_fmamk_f32 v172, v172, 0x3c000000, v187
	v_rsq_f32_e32 v172, v172
	v_add_f32_e32 v173, 1.0, v173
	v_rcp_f32_e32 v174, v173
	s_add_i32 s66, s40, 4
	v_pk_mul_f32 v[168:169], v[172:173], v[168:169] op_sel_hi:[0,1]
	v_mul_f32_e32 v172, 0xbfb8aa3b, v171
	v_exp_f32_e32 v172, v172
	v_pk_mul_f32 v[168:169], v[114:115], v[168:169]
	v_add_f32_e32 v172, 1.0, v172
	v_rcp_f32_e32 v175, v172
	s_nop 0
	v_pk_mul_f32 v[170:171], v[174:175], v[170:171]
	s_nop 0
	v_pk_mul_f32 v[168:169], v[170:171], v[168:169]
	s_nop 0
	v_cvt_pk_bf16_f32 v170, v168, v169
	v_lshl_add_u64 v[168:169], v[120:121], 0, s[64:65]
	global_store_dword v[168:169], v170, off
	v_pk_mul_f32 v[170:171], v[166:167], v[166:167]
	v_lshlrev_b32_e32 v168, 16, v233
	v_add_f32_e32 v170, v170, v171
	v_mov_b32_e32 v171, 0
	v_and_b32_e32 v169, 0xffff0000, v233
	v_add_f32_dpp v170, v170, v170 quad_perm:[1,0,3,2] row_mask:0xf bank_mask:0xf bound_ctrl:1
	s_nop 1
	v_add_f32_dpp v170, v170, v170 quad_perm:[2,3,0,1] row_mask:0xf bank_mask:0xf bound_ctrl:1
	s_nop 1
	v_add_f32_dpp v170, v170, v170 row_half_mirror row_mask:0xf bank_mask:0xf bound_ctrl:1
	s_nop 1
	v_add_f32_dpp v170, v170, v170 row_mirror row_mask:0xf bank_mask:0xf bound_ctrl:1
	s_nop 1
	v_mov_b32_dpp v171, v170 row_bcast:15 row_mask:0xa bank_mask:0xf bound_ctrl:1
	v_add_f32_e32 v170, v170, v171
	v_mul_f32_e32 v171, 0xbfb8aa3b, v168
	v_readlane_b32 s64, v170, 63
	v_readlane_b32 s41, v170, 31
	v_exp_f32_e32 v171, v171
	v_mov_b32_e32 v170, s64
	v_add_f32_e32 v170, s41, v170
	v_fmamk_f32 v170, v170, 0x3c000000, v187
	v_rsq_f32_e32 v170, v170
	v_add_f32_e32 v171, 1.0, v171
	v_rcp_f32_e32 v172, v171
	s_add_i32 s64, s40, 5
	v_pk_mul_f32 v[166:167], v[170:171], v[166:167] op_sel_hi:[0,1]
	v_mul_f32_e32 v170, 0xbfb8aa3b, v169
	v_exp_f32_e32 v170, v170
	v_pk_mul_f32 v[166:167], v[114:115], v[166:167]
	v_add_f32_e32 v170, 1.0, v170
	v_rcp_f32_e32 v173, v170
	s_nop 0
	v_pk_mul_f32 v[168:169], v[172:173], v[168:169]
	s_nop 0
	v_pk_mul_f32 v[166:167], v[168:169], v[166:167]
	s_nop 0
	v_cvt_pk_bf16_f32 v168, v166, v167
	v_lshl_add_u64 v[166:167], v[120:121], 0, s[62:63]
	global_store_dword v[166:167], v168, off
	v_pk_mul_f32 v[168:169], v[164:165], v[164:165]
	v_lshlrev_b32_e32 v166, 16, v232
	v_add_f32_e32 v168, v168, v169
	v_mov_b32_e32 v169, 0
	v_and_b32_e32 v167, 0xffff0000, v232
	v_add_f32_dpp v168, v168, v168 quad_perm:[1,0,3,2] row_mask:0xf bank_mask:0xf bound_ctrl:1
	s_nop 1
	v_add_f32_dpp v168, v168, v168 quad_perm:[2,3,0,1] row_mask:0xf bank_mask:0xf bound_ctrl:1
	s_nop 1
	v_add_f32_dpp v168, v168, v168 row_half_mirror row_mask:0xf bank_mask:0xf bound_ctrl:1
	s_nop 1
	v_add_f32_dpp v168, v168, v168 row_mirror row_mask:0xf bank_mask:0xf bound_ctrl:1
	s_nop 1
	v_mov_b32_dpp v169, v168 row_bcast:15 row_mask:0xa bank_mask:0xf bound_ctrl:1
	v_add_f32_e32 v168, v168, v169
	v_mul_f32_e32 v169, 0xbfb8aa3b, v166
	v_readlane_b32 s62, v168, 63
	v_readlane_b32 s41, v168, 31
	v_exp_f32_e32 v169, v169
	v_mov_b32_e32 v168, s62
	v_add_f32_e32 v168, s41, v168
	v_fmamk_f32 v168, v168, 0x3c000000, v187
	v_rsq_f32_e32 v168, v168
	v_add_f32_e32 v169, 1.0, v169
	v_rcp_f32_e32 v170, v169
	s_add_i32 s62, s40, 6
	v_pk_mul_f32 v[164:165], v[168:169], v[164:165] op_sel_hi:[0,1]
	v_mul_f32_e32 v168, 0xbfb8aa3b, v167
	v_exp_f32_e32 v168, v168
	v_pk_mul_f32 v[164:165], v[114:115], v[164:165]
	v_add_f32_e32 v168, 1.0, v168
	v_rcp_f32_e32 v171, v168
	s_nop 0
	v_pk_mul_f32 v[166:167], v[170:171], v[166:167]
	s_nop 0
	v_pk_mul_f32 v[164:165], v[166:167], v[164:165]
	s_nop 0
	v_cvt_pk_bf16_f32 v166, v164, v165
	v_lshl_add_u64 v[164:165], v[120:121], 0, s[60:61]
	global_store_dword v[164:165], v166, off
	v_add_u32_e32 v166, 0x800, v180
	ds_read2_b32 v[164:165], v166 offset0:16 offset1:82
	s_waitcnt lgkmcnt(0)
	v_lshlrev_b32_e32 v232, 16, v164
	v_and_b32_e32 v233, 0xffff0000, v164
	v_pk_mul_f32 v[238:239], v[232:233], v[232:233]
	v_lshlrev_b32_e32 v234, 16, v165
	v_add_f32_e32 v231, v238, v239
	v_mov_b32_e32 v238, 0
	v_and_b32_e32 v235, 0xffff0000, v165
	v_add_f32_dpp v231, v231, v231 quad_perm:[1,0,3,2] row_mask:0xf bank_mask:0xf bound_ctrl:1
	ds_read2_b32 v[164:165], v166 offset0:148 offset1:214
	v_add_u32_e32 v166, 0xc00, v180
	v_add_f32_dpp v231, v231, v231 quad_perm:[2,3,0,1] row_mask:0xf bank_mask:0xf bound_ctrl:1
	s_waitcnt lgkmcnt(0)
	v_lshlrev_b32_e32 v174, 16, v164
	v_add_f32_dpp v231, v231, v231 row_half_mirror row_mask:0xf bank_mask:0xf bound_ctrl:1
	v_and_b32_e32 v175, 0xffff0000, v164
	v_lshlrev_b32_e32 v172, 16, v165
	v_add_f32_dpp v231, v231, v231 row_mirror row_mask:0xf bank_mask:0xf bound_ctrl:1
	v_and_b32_e32 v173, 0xffff0000, v165
	ds_read2_b32 v[164:165], v166 offset0:24 offset1:90
	v_mov_b32_dpp v238, v231 row_bcast:15 row_mask:0xa bank_mask:0xf bound_ctrl:1
	v_add_f32_e32 v231, v231, v238
	s_waitcnt lgkmcnt(0)
	v_lshlrev_b32_e32 v170, 16, v164
	v_readlane_b32 s60, v231, 63
	v_readlane_b32 s41, v231, 31
	v_and_b32_e32 v171, 0xffff0000, v164
	v_mov_b32_e32 v231, s60
	v_add_f32_e32 v231, s41, v231
	v_fmamk_f32 v231, v231, 0x3c000000, v187
	v_rsq_f32_e32 v238, v231
	v_mul_f32_e32 v231, 0xbfb8aa3b, v236
	v_exp_f32_e32 v231, v231
	v_lshlrev_b32_e32 v168, 16, v165
	v_pk_mul_f32 v[232:233], v[238:239], v[232:233] op_sel_hi:[0,1]
	v_pk_mul_f32 v[232:233], v[114:115], v[232:233]
	v_add_f32_e32 v231, 1.0, v231
	v_rcp_f32_e32 v240, v231
	v_mul_f32_e32 v231, 0xbfb8aa3b, v237
	v_exp_f32_e32 v231, v231
	v_and_b32_e32 v169, 0xffff0000, v165
	ds_read2_b32 v[164:165], v166 offset0:156 offset1:222
	s_add_i32 s60, s40, 7
	v_add_f32_e32 v231, 1.0, v231
	v_rcp_f32_e32 v241, v231
	s_waitcnt lgkmcnt(0)
	v_lshlrev_b32_e32 v166, 16, v164
	v_and_b32_e32 v167, 0xffff0000, v164
	v_pk_mul_f32 v[236:237], v[240:241], v[236:237]
	v_lshlrev_b32_e32 v164, 16, v165
	v_pk_mul_f32 v[232:233], v[236:237], v[232:233]
	v_and_b32_e32 v165, 0xffff0000, v165
	v_cvt_pk_bf16_f32 v231, v232, v233
	v_lshl_add_u64 v[232:233], v[120:121], 0, s[58:59]
	global_store_dword v[232:233], v231, off
	s_waitcnt vmcnt(29)
	v_lshlrev_b32_e32 v232, 16, v230
	v_and_b32_e32 v233, 0xffff0000, v230
	v_pk_mul_f32 v[230:231], v[234:235], v[234:235]
	s_nop 0
	v_add_f32_e32 v230, v230, v231
	v_mov_b32_e32 v231, 0
	s_nop 0
	v_add_f32_dpp v230, v230, v230 quad_perm:[1,0,3,2] row_mask:0xf bank_mask:0xf bound_ctrl:1
	s_nop 1
	v_add_f32_dpp v230, v230, v230 quad_perm:[2,3,0,1] row_mask:0xf bank_mask:0xf bound_ctrl:1
	s_nop 1
	v_add_f32_dpp v230, v230, v230 row_half_mirror row_mask:0xf bank_mask:0xf bound_ctrl:1
	s_nop 1
	v_add_f32_dpp v230, v230, v230 row_mirror row_mask:0xf bank_mask:0xf bound_ctrl:1
	s_nop 1
	v_mov_b32_dpp v231, v230 row_bcast:15 row_mask:0xa bank_mask:0xf bound_ctrl:1
	v_add_f32_e32 v230, v230, v231
	v_mul_f32_e32 v231, 0xbfb8aa3b, v232
	v_readlane_b32 s58, v230, 63
	v_readlane_b32 s41, v230, 31
	v_exp_f32_e32 v231, v231
	v_mov_b32_e32 v230, s58
	v_add_f32_e32 v230, s41, v230
	v_fmamk_f32 v230, v230, 0x3c000000, v187
	v_rsq_f32_e32 v230, v230
	v_add_f32_e32 v231, 1.0, v231
	v_rcp_f32_e32 v236, v231
	s_add_i32 s58, s40, 8
	v_pk_mul_f32 v[230:231], v[230:231], v[234:235] op_sel_hi:[0,1]
	v_mul_f32_e32 v234, 0xbfb8aa3b, v233
	v_exp_f32_e32 v234, v234
	v_pk_mul_f32 v[230:231], v[114:115], v[230:231]
	v_add_f32_e32 v234, 1.0, v234
	v_rcp_f32_e32 v237, v234
	s_nop 0
	v_pk_mul_f32 v[232:233], v[236:237], v[232:233]
	s_nop 0
	v_pk_mul_f32 v[230:231], v[232:233], v[230:231]
	s_nop 0
	v_cvt_pk_bf16_f32 v232, v230, v231
	v_lshl_add_u64 v[230:231], v[120:121], 0, s[56:57]
	global_store_dword v[230:231], v232, off
	v_pk_mul_f32 v[232:233], v[174:175], v[174:175]
	s_waitcnt vmcnt(29)
	v_lshlrev_b32_e32 v230, 16, v229
	v_and_b32_e32 v231, 0xffff0000, v229
	v_add_f32_e32 v229, v232, v233
	v_mov_b32_e32 v232, 0
	s_nop 0
	v_add_f32_dpp v229, v229, v229 quad_perm:[1,0,3,2] row_mask:0xf bank_mask:0xf bound_ctrl:1
	s_nop 1
	v_add_f32_dpp v229, v229, v229 quad_perm:[2,3,0,1] row_mask:0xf bank_mask:0xf bound_ctrl:1
	s_nop 1
	v_add_f32_dpp v229, v229, v229 row_half_mirror row_mask:0xf bank_mask:0xf bound_ctrl:1
	s_nop 1
	v_add_f32_dpp v229, v229, v229 row_mirror row_mask:0xf bank_mask:0xf bound_ctrl:1
	s_nop 1
	v_mov_b32_dpp v232, v229 row_bcast:15 row_mask:0xa bank_mask:0xf bound_ctrl:1
	v_add_f32_e32 v229, v229, v232
	s_nop 0
	v_readlane_b32 s56, v229, 63
	v_readlane_b32 s41, v229, 31
	s_nop 0
	v_mov_b32_e32 v229, s56
	v_add_f32_e32 v229, s41, v229
	v_fmamk_f32 v229, v229, 0x3c000000, v187
	v_rsq_f32_e32 v232, v229
	v_mul_f32_e32 v229, 0xbfb8aa3b, v230
	v_exp_f32_e32 v229, v229
	s_add_i32 s56, s40, 9
	v_pk_mul_f32 v[174:175], v[232:233], v[174:175] op_sel_hi:[0,1]
	v_pk_mul_f32 v[174:175], v[114:115], v[174:175]
	v_add_f32_e32 v229, 1.0, v229
	v_rcp_f32_e32 v234, v229
	v_mul_f32_e32 v229, 0xbfb8aa3b, v231
	v_exp_f32_e32 v229, v229
	s_nop 0
	v_add_f32_e32 v229, 1.0, v229
	v_rcp_f32_e32 v235, v229
	s_nop 0
	v_pk_mul_f32 v[230:231], v[234:235], v[230:231]
	s_nop 0
	v_pk_mul_f32 v[174:175], v[230:231], v[174:175]
	s_nop 0
	v_cvt_pk_bf16_f32 v229, v174, v175
	v_lshl_add_u64 v[174:175], v[120:121], 0, s[54:55]
	global_store_dword v[174:175], v229, off
	s_waitcnt vmcnt(29)
	v_lshlrev_b32_e32 v174, 16, v228
	v_and_b32_e32 v175, 0xffff0000, v228
	v_pk_mul_f32 v[228:229], v[172:173], v[172:173]
	s_nop 0
	v_add_f32_e32 v228, v228, v229
	v_mov_b32_e32 v229, 0
	s_nop 0
	v_add_f32_dpp v228, v228, v228 quad_perm:[1,0,3,2] row_mask:0xf bank_mask:0xf bound_ctrl:1
	s_nop 1
	v_add_f32_dpp v228, v228, v228 quad_perm:[2,3,0,1] row_mask:0xf bank_mask:0xf bound_ctrl:1
	s_nop 1
	v_add_f32_dpp v228, v228, v228 row_half_mirror row_mask:0xf bank_mask:0xf bound_ctrl:1
	s_nop 1
	v_add_f32_dpp v228, v228, v228 row_mirror row_mask:0xf bank_mask:0xf bound_ctrl:1
	s_nop 1
	v_mov_b32_dpp v229, v228 row_bcast:15 row_mask:0xa bank_mask:0xf bound_ctrl:1
	v_add_f32_e32 v228, v228, v229
	v_mul_f32_e32 v229, 0xbfb8aa3b, v174
	v_readlane_b32 s54, v228, 63
	v_readlane_b32 s41, v228, 31
	v_exp_f32_e32 v229, v229
	v_mov_b32_e32 v228, s54
	v_add_f32_e32 v228, s41, v228
	v_fmamk_f32 v228, v228, 0x3c000000, v187
	v_rsq_f32_e32 v228, v228
	v_add_f32_e32 v229, 1.0, v229
	v_rcp_f32_e32 v230, v229
	s_add_i32 s54, s40, 10
	v_pk_mul_f32 v[172:173], v[228:229], v[172:173] op_sel_hi:[0,1]
	v_mul_f32_e32 v228, 0xbfb8aa3b, v175
	v_exp_f32_e32 v228, v228
	v_pk_mul_f32 v[172:173], v[114:115], v[172:173]
	v_add_f32_e32 v228, 1.0, v228
	v_rcp_f32_e32 v231, v228
	s_nop 0
	v_pk_mul_f32 v[174:175], v[230:231], v[174:175]
	s_nop 0
	v_pk_mul_f32 v[172:173], v[174:175], v[172:173]
	s_nop 0
	v_cvt_pk_bf16_f32 v174, v172, v173
	v_lshl_add_u64 v[172:173], v[120:121], 0, s[52:53]
	global_store_dword v[172:173], v174, off
	v_pk_mul_f32 v[174:175], v[170:171], v[170:171]
	s_waitcnt vmcnt(29)
	v_lshlrev_b32_e32 v172, 16, v227
	v_add_f32_e32 v174, v174, v175
	v_mov_b32_e32 v175, 0
	v_and_b32_e32 v173, 0xffff0000, v227
	v_add_f32_dpp v174, v174, v174 quad_perm:[1,0,3,2] row_mask:0xf bank_mask:0xf bound_ctrl:1
	s_nop 1
	v_add_f32_dpp v174, v174, v174 quad_perm:[2,3,0,1] row_mask:0xf bank_mask:0xf bound_ctrl:1
	s_nop 1
	v_add_f32_dpp v174, v174, v174 row_half_mirror row_mask:0xf bank_mask:0xf bound_ctrl:1
	s_nop 1
	v_add_f32_dpp v174, v174, v174 row_mirror row_mask:0xf bank_mask:0xf bound_ctrl:1
	s_nop 1
	v_mov_b32_dpp v175, v174 row_bcast:15 row_mask:0xa bank_mask:0xf bound_ctrl:1
	v_add_f32_e32 v174, v174, v175
	v_mul_f32_e32 v175, 0xbfb8aa3b, v172
	v_readlane_b32 s52, v174, 63
	v_readlane_b32 s41, v174, 31
	v_exp_f32_e32 v175, v175
	v_mov_b32_e32 v174, s52
	v_add_f32_e32 v174, s41, v174
	v_fmamk_f32 v174, v174, 0x3c000000, v187
	v_rsq_f32_e32 v174, v174
	v_add_f32_e32 v175, 1.0, v175
	v_rcp_f32_e32 v228, v175
	s_add_i32 s52, s40, 11
	v_pk_mul_f32 v[170:171], v[174:175], v[170:171] op_sel_hi:[0,1]
	v_mul_f32_e32 v174, 0xbfb8aa3b, v173
	v_exp_f32_e32 v174, v174
	v_pk_mul_f32 v[170:171], v[114:115], v[170:171]
	v_add_f32_e32 v174, 1.0, v174
	v_rcp_f32_e32 v229, v174
	s_nop 0
	v_pk_mul_f32 v[172:173], v[228:229], v[172:173]
	s_nop 0
	v_pk_mul_f32 v[170:171], v[172:173], v[170:171]
	s_nop 0
	v_cvt_pk_bf16_f32 v172, v170, v171
	v_lshl_add_u64 v[170:171], v[120:121], 0, s[50:51]
	global_store_dword v[170:171], v172, off
	v_pk_mul_f32 v[172:173], v[168:169], v[168:169]
	s_waitcnt vmcnt(29)
	v_lshlrev_b32_e32 v170, 16, v226
	v_add_f32_e32 v172, v172, v173
	v_mov_b32_e32 v173, 0
	v_and_b32_e32 v171, 0xffff0000, v226
	v_add_f32_dpp v172, v172, v172 quad_perm:[1,0,3,2] row_mask:0xf bank_mask:0xf bound_ctrl:1
	s_nop 1
	v_add_f32_dpp v172, v172, v172 quad_perm:[2,3,0,1] row_mask:0xf bank_mask:0xf bound_ctrl:1
	s_nop 1
	v_add_f32_dpp v172, v172, v172 row_half_mirror row_mask:0xf bank_mask:0xf bound_ctrl:1
	s_nop 1
	v_add_f32_dpp v172, v172, v172 row_mirror row_mask:0xf bank_mask:0xf bound_ctrl:1
	s_nop 1
	v_mov_b32_dpp v173, v172 row_bcast:15 row_mask:0xa bank_mask:0xf bound_ctrl:1
	v_add_f32_e32 v172, v172, v173
	v_mul_f32_e32 v173, 0xbfb8aa3b, v170
	v_readlane_b32 s50, v172, 63
	v_readlane_b32 s41, v172, 31
	v_exp_f32_e32 v173, v173
	v_mov_b32_e32 v172, s50
	v_add_f32_e32 v172, s41, v172
	v_fmamk_f32 v172, v172, 0x3c000000, v187
	v_rsq_f32_e32 v172, v172
	v_add_f32_e32 v173, 1.0, v173
	v_rcp_f32_e32 v174, v173
	s_add_i32 s50, s40, 12
	v_pk_mul_f32 v[168:169], v[172:173], v[168:169] op_sel_hi:[0,1]
	v_mul_f32_e32 v172, 0xbfb8aa3b, v171
	v_exp_f32_e32 v172, v172
	v_pk_mul_f32 v[168:169], v[114:115], v[168:169]
	v_add_f32_e32 v172, 1.0, v172
	v_rcp_f32_e32 v175, v172
	s_nop 0
	v_pk_mul_f32 v[170:171], v[174:175], v[170:171]
	s_nop 0
	v_pk_mul_f32 v[168:169], v[170:171], v[168:169]
	s_nop 0
	v_cvt_pk_bf16_f32 v170, v168, v169
	v_lshl_add_u64 v[168:169], v[120:121], 0, s[48:49]
	global_store_dword v[168:169], v170, off
	v_pk_mul_f32 v[170:171], v[166:167], v[166:167]
	s_waitcnt vmcnt(29)
	v_lshlrev_b32_e32 v168, 16, v225
	v_add_f32_e32 v170, v170, v171
	v_mov_b32_e32 v171, 0
	v_and_b32_e32 v169, 0xffff0000, v225
	v_add_f32_dpp v170, v170, v170 quad_perm:[1,0,3,2] row_mask:0xf bank_mask:0xf bound_ctrl:1
	s_nop 1
	v_add_f32_dpp v170, v170, v170 quad_perm:[2,3,0,1] row_mask:0xf bank_mask:0xf bound_ctrl:1
	s_nop 1
	v_add_f32_dpp v170, v170, v170 row_half_mirror row_mask:0xf bank_mask:0xf bound_ctrl:1
	s_nop 1
	v_add_f32_dpp v170, v170, v170 row_mirror row_mask:0xf bank_mask:0xf bound_ctrl:1
	s_nop 1
	v_mov_b32_dpp v171, v170 row_bcast:15 row_mask:0xa bank_mask:0xf bound_ctrl:1
	v_add_f32_e32 v170, v170, v171
	v_mul_f32_e32 v171, 0xbfb8aa3b, v168
	v_readlane_b32 s48, v170, 63
	v_readlane_b32 s41, v170, 31
	v_exp_f32_e32 v171, v171
	v_mov_b32_e32 v170, s48
	v_add_f32_e32 v170, s41, v170
	v_fmamk_f32 v170, v170, 0x3c000000, v187
	v_rsq_f32_e32 v170, v170
	v_add_f32_e32 v171, 1.0, v171
	v_rcp_f32_e32 v172, v171
	s_add_i32 s48, s40, 13
	v_pk_mul_f32 v[166:167], v[170:171], v[166:167] op_sel_hi:[0,1]
	v_mul_f32_e32 v170, 0xbfb8aa3b, v169
	v_exp_f32_e32 v170, v170
	v_pk_mul_f32 v[166:167], v[114:115], v[166:167]
	v_add_f32_e32 v170, 1.0, v170
	v_rcp_f32_e32 v173, v170
	s_nop 0
	v_pk_mul_f32 v[168:169], v[172:173], v[168:169]
	s_nop 0
	v_pk_mul_f32 v[166:167], v[168:169], v[166:167]
	s_nop 0
	v_cvt_pk_bf16_f32 v168, v166, v167
	v_lshl_add_u64 v[166:167], v[120:121], 0, s[46:47]
	global_store_dword v[166:167], v168, off
	v_pk_mul_f32 v[168:169], v[164:165], v[164:165]
	s_waitcnt vmcnt(29)
	v_lshlrev_b32_e32 v166, 16, v224
	v_add_f32_e32 v168, v168, v169
	v_mov_b32_e32 v169, 0
	v_and_b32_e32 v167, 0xffff0000, v224
	v_add_f32_dpp v168, v168, v168 quad_perm:[1,0,3,2] row_mask:0xf bank_mask:0xf bound_ctrl:1
	s_nop 1
	v_add_f32_dpp v168, v168, v168 quad_perm:[2,3,0,1] row_mask:0xf bank_mask:0xf bound_ctrl:1
	s_nop 1
	v_add_f32_dpp v168, v168, v168 row_half_mirror row_mask:0xf bank_mask:0xf bound_ctrl:1
	s_nop 1
	v_add_f32_dpp v168, v168, v168 row_mirror row_mask:0xf bank_mask:0xf bound_ctrl:1
	s_nop 1
	v_mov_b32_dpp v169, v168 row_bcast:15 row_mask:0xa bank_mask:0xf bound_ctrl:1
	v_add_f32_e32 v168, v168, v169
	v_mul_f32_e32 v169, 0xbfb8aa3b, v166
	v_readlane_b32 s46, v168, 63
	v_readlane_b32 s41, v168, 31
	v_exp_f32_e32 v169, v169
	v_mov_b32_e32 v168, s46
	v_add_f32_e32 v168, s41, v168
	v_fmamk_f32 v168, v168, 0x3c000000, v187
	v_rsq_f32_e32 v168, v168
	v_add_f32_e32 v169, 1.0, v169
	v_rcp_f32_e32 v170, v169
	s_add_i32 s46, s40, 14
	v_pk_mul_f32 v[164:165], v[168:169], v[164:165] op_sel_hi:[0,1]
	v_mul_f32_e32 v168, 0xbfb8aa3b, v167
	v_exp_f32_e32 v168, v168
	v_pk_mul_f32 v[164:165], v[114:115], v[164:165]
	v_add_f32_e32 v168, 1.0, v168
	v_rcp_f32_e32 v171, v168
	s_nop 0
	v_pk_mul_f32 v[166:167], v[170:171], v[166:167]
	s_nop 0
	v_pk_mul_f32 v[164:165], v[166:167], v[164:165]
	s_nop 0
	v_cvt_pk_bf16_f32 v166, v164, v165
	v_lshl_add_u64 v[164:165], v[120:121], 0, s[44:45]
	global_store_dword v[164:165], v166, off
	v_mad_i64_i32 v[164:165], s[44:45], s40, v188, v[116:117]
	global_load_dword v227, v[164:165], off
	v_mad_i64_i32 v[164:165], s[44:45], s72, v188, v[116:117]
	global_load_dword v226, v[164:165], off
	v_mad_i64_i32 v[164:165], s[44:45], s70, v188, v[116:117]
	global_load_dword v225, v[164:165], off
	v_mad_i64_i32 v[164:165], s[44:45], s68, v188, v[116:117]
	global_load_dword v224, v[164:165], off
	v_mad_i64_i32 v[164:165], s[44:45], s66, v188, v[116:117]
	global_load_dword v175, v[164:165], off
	v_mad_i64_i32 v[164:165], s[44:45], s64, v188, v[116:117]
	global_load_dword v174, v[164:165], off
	v_mad_i64_i32 v[164:165], s[44:45], s62, v188, v[116:117]
	global_load_dword v173, v[164:165], off
	v_mad_i64_i32 v[164:165], s[44:45], s60, v188, v[116:117]
	global_load_dword v172, v[164:165], off
	v_mad_i64_i32 v[164:165], s[44:45], s58, v188, v[116:117]
	global_load_dword v171, v[164:165], off
	v_mad_i64_i32 v[164:165], s[44:45], s56, v188, v[116:117]
	global_load_dword v170, v[164:165], off
	v_mad_i64_i32 v[164:165], s[44:45], s54, v188, v[116:117]
	global_load_dword v169, v[164:165], off
	v_mad_i64_i32 v[164:165], s[44:45], s52, v188, v[116:117]
	global_load_dword v168, v[164:165], off
	v_mad_i64_i32 v[164:165], s[44:45], s50, v188, v[116:117]
	global_load_dword v167, v[164:165], off
	v_mad_i64_i32 v[164:165], s[44:45], s48, v188, v[116:117]
	global_load_dword v166, v[164:165], off
	v_mad_i64_i32 v[164:165], s[44:45], s46, v188, v[116:117]
	s_add_i32 s44, s40, 15
	s_nop 0
	v_mad_i64_i32 v[228:229], s[74:75], s44, v188, v[116:117]
	global_load_dword v165, v[164:165], off
	s_cmp_gt_u32 s29, 60
	global_load_dword v164, v[228:229], off
	s_cbranch_scc1 .Lscan_skip_b
	v_add_co_u32_e32 v42, vcc, 0x2e40c000, v162
	v_add_u32_e32 v50, 0xc0, v223
	s_nop 0
	v_addc_co_u32_e32 v43, vcc, 0, v163, vcc
	v_add_co_u32_e32 v58, vcc, 0x2e40c000, v160
	v_add_u32_e32 v62, 0xc0, v222
	s_nop 0
	v_addc_co_u32_e32 v59, vcc, 0, v161, vcc
	v_add_co_u32_e32 v74, vcc, 0x2e40c000, v158
	v_add_u32_e32 v78, 0xc0, v221
	s_nop 0
	v_addc_co_u32_e32 v75, vcc, 0, v159, vcc
	v_add_co_u32_e32 v82, vcc, 0x2e40c000, v156
	v_add_u32_e32 v86, 0xc0, v220
	s_nop 0
	v_addc_co_u32_e32 v83, vcc, 0, v157, vcc
	v_add_co_u32_e32 v98, vcc, s78, v154
	v_ashrrev_i32_e32 v51, 31, v50
	s_nop 0
	v_addc_co_u32_e32 v99, vcc, 0, v155, vcc
	v_add_co_u32_e32 v102, vcc, s78, v152
	v_ashrrev_i32_e32 v63, 31, v62
	s_nop 0
	v_addc_co_u32_e32 v103, vcc, 0, v153, vcc
	v_add_co_u32_e32 v106, vcc, 0x1120c000, v150
	v_ashrrev_i32_e32 v79, 31, v78
	v_ashrrev_i32_e32 v87, 31, v86
	v_addc_co_u32_e32 v107, vcc, 0, v151, vcc
	v_lshlrev_b64 v[50:51], 12, v[50:51]
	v_lshlrev_b64 v[62:63], 12, v[62:63]
	v_lshlrev_b64 v[78:79], 12, v[78:79]
	v_lshlrev_b64 v[86:87], 12, v[86:87]
	v_add_co_u32_e32 v110, vcc, 0x1120c000, v148
	v_lshl_add_u64 v[50:51], v[118:119], 0, v[50:51]
	v_lshl_add_u64 v[62:63], v[118:119], 0, v[62:63]
	v_lshl_add_u64 v[78:79], v[118:119], 0, v[78:79]
	v_lshl_add_u64 v[86:87], v[118:119], 0, v[86:87]
	v_lshl_add_u64 v[90:91], v[144:145], 0, v[178:179]
	v_lshl_add_u64 v[94:95], v[146:147], 0, v[178:179]
	v_addc_co_u32_e32 v111, vcc, 0, v149, vcc
	global_load_dwordx4 v[42:45], v[42:43], off
	v_mov_b32_e32 v219, 0
	global_load_dwordx4 v[50:53], v[50:51], off
	v_mov_b32_e32 v185, 0
	global_load_dwordx4 v[58:61], v[58:59], off
	s_nop 0
	global_load_dwordx4 v[62:65], v[62:63], off
	s_nop 0
	global_load_dwordx4 v[74:77], v[74:75], off
	s_nop 0
	global_load_dwordx4 v[78:81], v[78:79], off
	s_nop 0
	global_load_dwordx4 v[82:85], v[82:83], off
	s_nop 0
	global_load_dwordx4 v[86:89], v[86:87], off
	s_nop 0
	global_load_dwordx4 v[90:93], v[90:91], off
	s_nop 0
	global_load_dwordx4 v[94:97], v[94:95], off
	s_nop 0
	global_load_dwordx4 v[98:101], v[98:99], off
	s_nop 0
	global_load_dwordx4 v[102:105], v[102:103], off
	s_nop 0
	global_load_dwordx4 v[106:109], v[106:107], off
	s_nop 0
	global_load_dwordx4 v[110:113], v[110:111], off
	s_and_saveexec_b64 s[74:75], s[0:1]
	s_cbranch_execz .LBB0_865
	v_lshl_add_u64 v[148:149], s[36:37], 0, v[130:131]
	global_load_dword v219, v[148:149], off offset:256
	global_load_dword v185, v179, s[36:37] offset:1532

.LBB0_866:
	s_ashr_i32 s41, s40, 31
	s_ashr_i32 s73, s72, 31
	s_ashr_i32 s71, s70, 31
	s_ashr_i32 s69, s68, 31
	s_ashr_i32 s67, s66, 31
	s_ashr_i32 s65, s64, 31
	s_ashr_i32 s63, s62, 31
	s_ashr_i32 s61, s60, 31
	s_ashr_i32 s59, s58, 31
	s_ashr_i32 s57, s56, 31
	s_ashr_i32 s55, s54, 31
	s_ashr_i32 s53, s52, 31
	s_ashr_i32 s51, s50, 31
	s_ashr_i32 s49, s48, 31
	s_ashr_i32 s47, s46, 31
	s_andn2_b64 vcc, exec, s[42:43]
	s_ashr_i32 s45, s44, 31
	s_cbranch_vccnz .LBB0_855
	s_waitcnt vmcnt(46)
	ds_write2_b64 v192, v[2:3], v[4:5] offset1:1
	ds_write2_b64 v193, v[6:7], v[8:9] offset1:1
	ds_write2_b64 v195, v[10:11], v[12:13] offset1:1
	ds_write2_b64 v196, v[14:15], v[16:17] offset1:1
	ds_write2_b64 v198, v[18:19], v[20:21] offset1:1
	ds_write2_b64 v199, v[22:23], v[24:25] offset1:1
	ds_write2_b64 v201, v[26:27], v[28:29] offset1:1
	ds_write2_b64 v202, v[30:31], v[32:33] offset1:1
	ds_write2_b64 v204, v[34:35], v[36:37] offset1:1
	ds_write2_b64 v206, v[38:39], v[40:41] offset1:1
	ds_write2_b64 v207, v[46:47], v[48:49] offset1:1
	ds_write2_b64 v208, v[54:55], v[56:57] offset1:1
	ds_write2_b64 v210, v[66:67], v[68:69] offset1:1
	ds_write2_b64 v212, v[70:71], v[72:73] offset1:1
	s_and_saveexec_b64 s[42:43], s[0:1]
	s_cbranch_execz .LBB0_854
	v_sub_f32_e32 v148, v189, v184
	v_mul_f32_e32 v149, 0x3fb8aa3b, v184
	v_mul_f32_e32 v148, 0x3fb8aa3b, v148
	v_exp_f32_e32 v149, v149
	v_exp_f32_e32 v148, v148
	v_mul_f32_e32 v149, 0x3db504f3, v149
	ds_write2st64_b32 v213, v149, v148 offset0:230 offset1:231
	s_branch .LBB0_854
.Lscan_skip_a:
	s_waitcnt vmcnt(0)
	s_branch .LBB0_860
